# A/B at identical code placement: every s_setprio in the GEMM main loops replaced by a same-size s_nop (priority flips off)
# baseline (speedup 1.0000x reference)
; #define PG8_STAGE(bufoff, gbase, voff) do { _Pragma("unroll") for (int _i = 0; _i < 2; ++_i) \
;         __builtin_amdgcn_global_load_lds((const unsigned*)((const char*)(gbase) + (voff)[_i]), (LAS unsigned*)(lds + (bufoff) + ldsw + _i * 8192), 16, 0, 0); } while (0)
; #define PG8_LDA(dst, b, h) do { _Pragma("unroll") for (int m = 0; m < 4; ++m) _Pragma("unroll") for (int k = 0; k < 2; ++k) dst[m][k] = *(const LAS bf16x8*)(lds + PG8_SA(b, h) + aoff + m * 2048 + k * 1024); } while (0)
; #define PG8_LDB(dst, b, h) do { _Pragma("unroll") for (int n = 0; n < 2; ++n) _Pragma("unroll") for (int k = 0; k < 2; ++k) dst[n][k] = *(const LAS bf16x8*)(lds + PG8_SB(b, h) + boff + n * 2048 + k * 1024); } while (0)
; #define PG8_MMA(ai, bj, At, Bt) do { __builtin_amdgcn_s_setprio(1); _Pragma("unroll") for (int m = 0; m < 4; ++m) _Pragma("unroll") for (int n = 0; n < 2; ++n) _Pragma("unroll") for (int k = 0; k < 2; ++k) \
;         acc[ai][bj][m][n] = __builtin_amdgcn_mfma_f32_16x16x32_bf16(Bt[n][k], At[m][k], acc[ai][bj][m][n], 0, 0, 0); __builtin_amdgcn_s_setprio(0); } while (0)
; #define PG8_WAIT_V(n) asm volatile("s_waitcnt vmcnt(" #n ")" ::: "memory")
; #define PG8_WAIT_L(n) asm volatile("s_waitcnt lgkmcnt(" #n ")" ::: "memory")
; #define PG8_BAR __builtin_amdgcn_s_barrier()
; #define PG8_SCHED __builtin_amdgcn_sched_barrier(0)
; template <class Epi, class Sched>
; __device__ __forceinline__ void gemm_phase(LAS unsigned char* lds, const Gemm g, const Sched& S, const Epi& E, const int wave_s) {
;     ...
;             const bool last = (t == nt - 2);
;             const char* a1 = cA + (size_t)(t + 1) * kstep;
;             const char* a2 = last ? nA : cA + (size_t)(t + 2) * kstep; const char* b2 = last ? nB : cB + (size_t)(t + 2) * kstep;
;             const char* a3 = a2 + kstep; const char* b3 = b2 + kstep;
;             PG8_LDB(B0, 0, 0); PG8_LDB(B1, 0, 1); PG8_SCHED; PG8_LDA(At, 0, 0); PG8_STAGE(PG8_SA(1, 1), a1 + hstepA, voffA);
;             PG8_WAIT_V(8); PG8_WAIT_L(0); PG8_BAR; PG8_MMA(0, 0, At, B0); PG8_MMA(0, 1, At, B1); PG8_BAR; PG8_SCHED;
;             PG8_LDA(At, 0, 1); PG8_STAGE(PG8_SB(0, 0), b2, voffB); PG8_STAGE(PG8_SB(0, 1), b2 + hstepB, voffB); PG8_STAGE(PG8_SA(0, 0), a2, voffA);
;             PG8_WAIT_V(8); PG8_WAIT_L(0); PG8_BAR; PG8_MMA(1, 0, At, B0); PG8_MMA(1, 1, At, B1); PG8_BAR; PG8_SCHED;
.LBB0_125:
	ds_read_b128 v[152:155], v149
	ds_read_b128 v[156:159], v149 offset:1024
	ds_read_b128 v[160:163], v149 offset:2048
	ds_read_b128 v[164:167], v149 offset:3072
	ds_read_b128 v[168:171], v150
	ds_read_b128 v[172:175], v150 offset:1024
	ds_read_b128 v[176:179], v150 offset:2048
	ds_read_b128 v[180:183], v150 offset:3072
	s_add_u32 s4, s44, 0xfffc0080
	s_addc_u32 s5, s45, -1
	s_cmp_eq_u32 s65, 12
	s_cselect_b32 s47, s29, s5
	s_cselect_b32 s46, s61, s4
	s_cselect_b32 s5, s27, s64
	s_cselect_b32 s4, s62, s63
	v_lshl_add_u64 v[144:145], s[44:45], 0, v[136:137]
	s_add_i32 m0, s33, 0xc000
	ds_read_b128 v[184:187], v151
	ds_read_b128 v[188:191], v151 offset:1024
	ds_read_b128 v[192:195], v151 offset:2048
	ds_read_b128 v[196:199], v151 offset:3072
	ds_read_b128 v[200:203], v151 offset:4096
	ds_read_b128 v[204:207], v151 offset:5120
	ds_read_b128 v[210:213], v151 offset:6144
	ds_read_b128 v[214:217], v151 offset:7168
	global_load_lds_dwordx4 v[144:145], off
	v_lshl_add_u64 v[144:145], s[44:45], 0, v[138:139]
	s_add_i32 m0, s33, 0xe000
	s_nop 0
	global_load_lds_dwordx4 v[144:145], off
	s_waitcnt vmcnt(8) lgkmcnt(0)
	s_barrier
	s_nop 0
	v_mfma_f32_16x16x32_bf16 v[124:127], v[152:155], v[184:187], v[124:127]
	v_mfma_f32_16x16x32_bf16 v[120:123], v[160:163], v[184:187], v[120:123]
	v_mfma_f32_16x16x32_bf16 v[116:119], v[152:155], v[192:195], v[116:119]
	v_mfma_f32_16x16x32_bf16 v[108:111], v[160:163], v[192:195], v[108:111]
	v_mfma_f32_16x16x32_bf16 v[100:103], v[152:155], v[200:203], v[100:103]
	v_mfma_f32_16x16x32_bf16 v[92:95], v[160:163], v[200:203], v[92:95]
	v_mfma_f32_16x16x32_bf16 v[84:87], v[152:155], v[210:213], v[84:87]
	v_mfma_f32_16x16x32_bf16 v[76:79], v[160:163], v[210:213], v[76:79]
	v_mfma_f32_16x16x32_bf16 v[124:127], v[156:159], v[188:191], v[124:127]
	v_mfma_f32_16x16x32_bf16 v[120:123], v[164:167], v[188:191], v[120:123]
	v_mfma_f32_16x16x32_bf16 v[116:119], v[156:159], v[196:199], v[116:119]
	v_mfma_f32_16x16x32_bf16 v[108:111], v[164:167], v[196:199], v[108:111]
	v_mfma_f32_16x16x32_bf16 v[100:103], v[156:159], v[204:207], v[100:103]
	v_mfma_f32_16x16x32_bf16 v[92:95], v[164:167], v[204:207], v[92:95]
	v_mfma_f32_16x16x32_bf16 v[84:87], v[156:159], v[214:217], v[84:87]
	v_mfma_f32_16x16x32_bf16 v[76:79], v[164:167], v[214:217], v[76:79]
	s_nop 0
	s_nop 0
	v_mfma_f32_16x16x32_bf16 v[112:115], v[168:171], v[184:187], v[112:115]
	v_mfma_f32_16x16x32_bf16 v[104:107], v[176:179], v[184:187], v[104:107]
	v_mfma_f32_16x16x32_bf16 v[96:99], v[168:171], v[192:195], v[96:99]
	v_mfma_f32_16x16x32_bf16 v[88:91], v[176:179], v[192:195], v[88:91]
	v_mfma_f32_16x16x32_bf16 v[80:83], v[168:171], v[200:203], v[80:83]
	v_mfma_f32_16x16x32_bf16 v[72:75], v[176:179], v[200:203], v[72:75]
	v_mfma_f32_16x16x32_bf16 v[68:71], v[168:171], v[210:213], v[68:71]
	v_mfma_f32_16x16x32_bf16 v[64:67], v[176:179], v[210:213], v[64:67]
	v_mfma_f32_16x16x32_bf16 v[112:115], v[172:175], v[188:191], v[112:115]
	v_mfma_f32_16x16x32_bf16 v[104:107], v[180:183], v[188:191], v[104:107]
	v_mfma_f32_16x16x32_bf16 v[96:99], v[172:175], v[196:199], v[96:99]
	v_mfma_f32_16x16x32_bf16 v[88:91], v[180:183], v[196:199], v[88:91]
	v_mfma_f32_16x16x32_bf16 v[80:83], v[172:175], v[204:207], v[80:83]
	v_mfma_f32_16x16x32_bf16 v[72:75], v[180:183], v[204:207], v[72:75]
	v_mfma_f32_16x16x32_bf16 v[68:71], v[172:175], v[214:217], v[68:71]
	v_mfma_f32_16x16x32_bf16 v[64:67], v[180:183], v[214:217], v[64:67]
	s_nop 0
	s_barrier
	s_add_i32 s66, s53, s81
	v_lshl_add_u64 v[144:145], s[4:5], 0, v[130:131]
	s_mov_b32 m0, s66
	ds_read_b128 v[184:187], v151 offset:16384
	ds_read_b128 v[188:191], v151 offset:17408
	ds_read_b128 v[192:195], v151 offset:18432
	ds_read_b128 v[196:199], v151 offset:19456
	ds_read_b128 v[200:203], v151 offset:20480
	ds_read_b128 v[204:207], v151 offset:21504
	ds_read_b128 v[210:213], v151 offset:22528
	ds_read_b128 v[214:217], v151 offset:23552
	global_load_lds_dwordx4 v[144:145], off
	s_add_i32 m0, s66, 0x2000
	s_add_u32 s66, s4, 0x40000
	v_lshl_add_u64 v[218:219], s[4:5], 0, v[134:135]
	s_addc_u32 s67, s5, 0
	s_add_i32 s68, s54, s81
	global_load_lds_dwordx4 v[218:219], off
	v_lshl_add_u64 v[220:221], s[66:67], 0, v[130:131]
	s_mov_b32 m0, s68
	v_lshl_add_u64 v[222:223], s[46:47], 0, v[132:133]
	global_load_lds_dwordx4 v[220:221], off
	v_lshl_add_u64 v[220:221], s[66:67], 0, v[134:135]
	s_add_i32 m0, s68, 0x2000
	s_nop 0
	global_load_lds_dwordx4 v[220:221], off
	v_lshl_add_u64 v[220:221], s[46:47], 0, v[128:129]
	s_mov_b32 m0, s33
	s_nop 0
	global_load_lds_dwordx4 v[220:221], off
	s_mov_b32 m0, s35
	s_nop 0
	global_load_lds_dwordx4 v[222:223], off
	s_waitcnt vmcnt(8) lgkmcnt(0)
	s_barrier
; #define PG8_STAGE(bufoff, gbase, voff) do { _Pragma("unroll") for (int _i = 0; _i < 2; ++_i) \
;         __builtin_amdgcn_global_load_lds((const unsigned*)((const char*)(gbase) + (voff)[_i]), (LAS unsigned*)(lds + (bufoff) + ldsw + _i * 8192), 16, 0, 0); } while (0)
; #define PG8_LDA(dst, b, h) do { _Pragma("unroll") for (int m = 0; m < 4; ++m) _Pragma("unroll") for (int k = 0; k < 2; ++k) dst[m][k] = *(const LAS bf16x8*)(lds + PG8_SA(b, h) + aoff + m * 2048 + k * 1024); } while (0)
; #define PG8_LDB(dst, b, h) do { _Pragma("unroll") for (int n = 0; n < 2; ++n) _Pragma("unroll") for (int k = 0; k < 2; ++k) dst[n][k] = *(const LAS bf16x8*)(lds + PG8_SB(b, h) + boff + n * 2048 + k * 1024); } while (0)
; #define PG8_MMA(ai, bj, At, Bt) do { __builtin_amdgcn_s_setprio(1); _Pragma("unroll") for (int m = 0; m < 4; ++m) _Pragma("unroll") for (int n = 0; n < 2; ++n) _Pragma("unroll") for (int k = 0; k < 2; ++k) \
;         acc[ai][bj][m][n] = __builtin_amdgcn_mfma_f32_16x16x32_bf16(Bt[n][k], At[m][k], acc[ai][bj][m][n], 0, 0, 0); __builtin_amdgcn_s_setprio(0); } while (0)
; #define PG8_WAIT_V(n) asm volatile("s_waitcnt vmcnt(" #n ")" ::: "memory")
; #define PG8_WAIT_L(n) asm volatile("s_waitcnt lgkmcnt(" #n ")" ::: "memory")
; #define PG8_BAR __builtin_amdgcn_s_barrier()
; #define PG8_SCHED __builtin_amdgcn_sched_barrier(0)
; template <class Epi, class Sched>
; __device__ __forceinline__ void gemm_phase(LAS unsigned char* lds, const Gemm g, const Sched& S, const Epi& E, const int wave_s) {
;     ...
;             PG8_WAIT_V(8); PG8_WAIT_L(0); PG8_BAR; PG8_MMA(1, 0, At, B0); PG8_MMA(1, 1, At, B1); PG8_BAR; PG8_SCHED;
;             PG8_LDB(B0, 1, 0); PG8_LDB(B1, 1, 1); PG8_SCHED; PG8_LDA(At, 1, 0); PG8_STAGE(PG8_SA(0, 1), a2 + hstepA, voffA);
;             PG8_WAIT_V(8); PG8_WAIT_L(0); PG8_BAR; PG8_MMA(0, 0, At, B0); PG8_MMA(0, 1, At, B1); PG8_BAR; PG8_SCHED;
	s_nop 0
	v_mfma_f32_16x16x32_bf16 v[60:63], v[152:155], v[184:187], v[60:63]
	v_mfma_f32_16x16x32_bf16 v[56:59], v[160:163], v[184:187], v[56:59]
	v_mfma_f32_16x16x32_bf16 v[52:55], v[152:155], v[192:195], v[52:55]
	v_mfma_f32_16x16x32_bf16 v[44:47], v[160:163], v[192:195], v[44:47]
	v_mfma_f32_16x16x32_bf16 v[36:39], v[152:155], v[200:203], v[36:39]
	v_mfma_f32_16x16x32_bf16 v[28:31], v[160:163], v[200:203], v[28:31]
	v_mfma_f32_16x16x32_bf16 v[20:23], v[152:155], v[210:213], v[20:23]
	v_mfma_f32_16x16x32_bf16 v[12:15], v[160:163], v[210:213], v[12:15]
	v_mfma_f32_16x16x32_bf16 v[60:63], v[156:159], v[188:191], v[60:63]
	v_mfma_f32_16x16x32_bf16 v[56:59], v[164:167], v[188:191], v[56:59]
	v_mfma_f32_16x16x32_bf16 v[52:55], v[156:159], v[196:199], v[52:55]
	v_mfma_f32_16x16x32_bf16 v[44:47], v[164:167], v[196:199], v[44:47]
	v_mfma_f32_16x16x32_bf16 v[36:39], v[156:159], v[204:207], v[36:39]
	v_mfma_f32_16x16x32_bf16 v[28:31], v[164:167], v[204:207], v[28:31]
	v_mfma_f32_16x16x32_bf16 v[20:23], v[156:159], v[214:217], v[20:23]
	v_mfma_f32_16x16x32_bf16 v[12:15], v[164:167], v[214:217], v[12:15]
	s_nop 0
	s_nop 0
	v_mfma_f32_16x16x32_bf16 v[48:51], v[168:171], v[184:187], v[48:51]
	v_mfma_f32_16x16x32_bf16 v[40:43], v[176:179], v[184:187], v[40:43]
	v_mfma_f32_16x16x32_bf16 v[32:35], v[168:171], v[192:195], v[32:35]
	v_mfma_f32_16x16x32_bf16 v[24:27], v[176:179], v[192:195], v[24:27]
	v_mfma_f32_16x16x32_bf16 v[16:19], v[168:171], v[200:203], v[16:19]
	v_mfma_f32_16x16x32_bf16 v[8:11], v[176:179], v[200:203], v[8:11]
	v_mfma_f32_16x16x32_bf16 v[4:7], v[168:171], v[210:213], v[4:7]
	v_mfma_f32_16x16x32_bf16 v[0:3], v[176:179], v[210:213], v[0:3]
	v_mfma_f32_16x16x32_bf16 v[48:51], v[172:175], v[188:191], v[48:51]
	v_mfma_f32_16x16x32_bf16 v[40:43], v[180:183], v[188:191], v[40:43]
	v_mfma_f32_16x16x32_bf16 v[32:35], v[172:175], v[196:199], v[32:35]
	v_mfma_f32_16x16x32_bf16 v[24:27], v[180:183], v[196:199], v[24:27]
	v_mfma_f32_16x16x32_bf16 v[16:19], v[172:175], v[204:207], v[16:19]
	v_mfma_f32_16x16x32_bf16 v[8:11], v[180:183], v[204:207], v[8:11]
	v_mfma_f32_16x16x32_bf16 v[4:7], v[172:175], v[214:217], v[4:7]
	v_mfma_f32_16x16x32_bf16 v[0:3], v[180:183], v[214:217], v[0:3]
	s_nop 0
	s_barrier
	s_add_i32 s66, 0, 0x18000
	s_add_i32 s67, 0, 0x1c000
	v_add_u32_e32 v164, s66, v147
	v_add_u32_e32 v180, s67, v147
	ds_read_b128 v[152:155], v164
	ds_read_b128 v[156:159], v164 offset:1024
	ds_read_b128 v[160:163], v164 offset:2048
	ds_read_b128 v[164:167], v164 offset:3072
	ds_read_b128 v[168:171], v180
	ds_read_b128 v[172:175], v180 offset:1024
	ds_read_b128 v[176:179], v180 offset:2048
	ds_read_b128 v[180:183], v180 offset:3072
	s_add_u32 s46, s46, 0x40000
	s_addc_u32 s47, s47, 0
	s_mov_b32 m0, s37
	v_lshl_add_u64 v[224:225], s[46:47], 0, v[128:129]
	ds_read_b128 v[184:187], v151 offset:32768
	ds_read_b128 v[188:191], v151 offset:33792
	ds_read_b128 v[192:195], v151 offset:34816
	ds_read_b128 v[196:199], v151 offset:35840
	ds_read_b128 v[200:203], v151 offset:36864
	ds_read_b128 v[204:207], v151 offset:37888
	ds_read_b128 v[210:213], v151 offset:38912
	ds_read_b128 v[214:217], v151 offset:39936
	global_load_lds_dwordx4 v[224:225], off
	v_lshl_add_u64 v[224:225], s[46:47], 0, v[132:133]
	s_mov_b32 m0, s43
	s_nop 0
	global_load_lds_dwordx4 v[224:225], off
	s_waitcnt vmcnt(8) lgkmcnt(0)
	s_barrier
	s_nop 0
	v_mfma_f32_16x16x32_bf16 v[124:127], v[152:155], v[184:187], v[124:127]
	v_mfma_f32_16x16x32_bf16 v[120:123], v[160:163], v[184:187], v[120:123]
	v_mfma_f32_16x16x32_bf16 v[116:119], v[152:155], v[192:195], v[116:119]
	v_mfma_f32_16x16x32_bf16 v[108:111], v[160:163], v[192:195], v[108:111]
	v_mfma_f32_16x16x32_bf16 v[100:103], v[152:155], v[200:203], v[100:103]
	v_mfma_f32_16x16x32_bf16 v[92:95], v[160:163], v[200:203], v[92:95]
	v_mfma_f32_16x16x32_bf16 v[84:87], v[152:155], v[210:213], v[84:87]
	v_mfma_f32_16x16x32_bf16 v[76:79], v[160:163], v[210:213], v[76:79]
	v_mfma_f32_16x16x32_bf16 v[124:127], v[156:159], v[188:191], v[124:127]
	v_mfma_f32_16x16x32_bf16 v[120:123], v[164:167], v[188:191], v[120:123]
	v_mfma_f32_16x16x32_bf16 v[116:119], v[156:159], v[196:199], v[116:119]
	v_mfma_f32_16x16x32_bf16 v[108:111], v[164:167], v[196:199], v[108:111]
	v_mfma_f32_16x16x32_bf16 v[100:103], v[156:159], v[204:207], v[100:103]
	v_mfma_f32_16x16x32_bf16 v[92:95], v[164:167], v[204:207], v[92:95]
	v_mfma_f32_16x16x32_bf16 v[84:87], v[156:159], v[214:217], v[84:87]
	v_mfma_f32_16x16x32_bf16 v[76:79], v[164:167], v[214:217], v[76:79]
	s_nop 0
	s_nop 0
	v_mfma_f32_16x16x32_bf16 v[112:115], v[168:171], v[184:187], v[112:115]
	v_mfma_f32_16x16x32_bf16 v[104:107], v[176:179], v[184:187], v[104:107]
	v_mfma_f32_16x16x32_bf16 v[96:99], v[168:171], v[192:195], v[96:99]
	v_mfma_f32_16x16x32_bf16 v[88:91], v[176:179], v[192:195], v[88:91]
	v_mfma_f32_16x16x32_bf16 v[80:83], v[168:171], v[200:203], v[80:83]
	v_mfma_f32_16x16x32_bf16 v[72:75], v[176:179], v[200:203], v[72:75]
	v_mfma_f32_16x16x32_bf16 v[68:71], v[168:171], v[210:213], v[68:71]
	v_mfma_f32_16x16x32_bf16 v[64:67], v[176:179], v[210:213], v[64:67]
	v_mfma_f32_16x16x32_bf16 v[112:115], v[172:175], v[188:191], v[112:115]
	v_mfma_f32_16x16x32_bf16 v[104:107], v[180:183], v[188:191], v[104:107]
	v_mfma_f32_16x16x32_bf16 v[96:99], v[172:175], v[196:199], v[96:99]
	v_mfma_f32_16x16x32_bf16 v[88:91], v[180:183], v[196:199], v[88:91]
	v_mfma_f32_16x16x32_bf16 v[80:83], v[172:175], v[204:207], v[80:83]
	v_mfma_f32_16x16x32_bf16 v[72:75], v[180:183], v[204:207], v[72:75]
	v_mfma_f32_16x16x32_bf16 v[68:71], v[172:175], v[214:217], v[68:71]
	v_mfma_f32_16x16x32_bf16 v[64:67], v[180:183], v[214:217], v[64:67]
	s_nop 0
	s_barrier
; #define PG8_STAGE(bufoff, gbase, voff) do { _Pragma("unroll") for (int _i = 0; _i < 2; ++_i) \
;         __builtin_amdgcn_global_load_lds((const unsigned*)((const char*)(gbase) + (voff)[_i]), (LAS unsigned*)(lds + (bufoff) + ldsw + _i * 8192), 16, 0, 0); } while (0)
; #define PG8_LDA(dst, b, h) do { _Pragma("unroll") for (int m = 0; m < 4; ++m) _Pragma("unroll") for (int k = 0; k < 2; ++k) dst[m][k] = *(const LAS bf16x8*)(lds + PG8_SA(b, h) + aoff + m * 2048 + k * 1024); } while (0)
; #define PG8_MMA(ai, bj, At, Bt) do { __builtin_amdgcn_s_setprio(1); _Pragma("unroll") for (int m = 0; m < 4; ++m) _Pragma("unroll") for (int n = 0; n < 2; ++n) _Pragma("unroll") for (int k = 0; k < 2; ++k) \
;         acc[ai][bj][m][n] = __builtin_amdgcn_mfma_f32_16x16x32_bf16(Bt[n][k], At[m][k], acc[ai][bj][m][n], 0, 0, 0); __builtin_amdgcn_s_setprio(0); } while (0)
; #define PG8_WAIT_V(n) asm volatile("s_waitcnt vmcnt(" #n ")" ::: "memory")
; #define PG8_WAIT_L(n) asm volatile("s_waitcnt lgkmcnt(" #n ")" ::: "memory")
; #define PG8_BAR __builtin_amdgcn_s_barrier()
; #define PG8_SCHED __builtin_amdgcn_sched_barrier(0)
; template <class Epi, class Sched>
; __device__ __forceinline__ void gemm_phase(LAS unsigned char* lds, const Gemm g, const Sched& S, const Epi& E, const int wave_s) {
;     ...
;             PG8_LDA(At, 1, 1); PG8_STAGE(PG8_SB(1, 0), b3, voffB); PG8_STAGE(PG8_SB(1, 1), b3 + hstepB, voffB); PG8_STAGE(PG8_SA(1, 0), a3, voffA);
;             PG8_WAIT_V(8); PG8_WAIT_L(0); PG8_BAR; PG8_MMA(1, 0, At, B0); PG8_MMA(1, 1, At, B1); PG8_BAR; PG8_SCHED;
;         }
	s_add_i32 s46, s66, s81
	v_lshl_add_u64 v[144:145], v[144:145], 0, s[14:15]
	s_mov_b32 m0, s46
	ds_read_b128 v[184:187], v151 offset:49152
	ds_read_b128 v[188:191], v151 offset:50176
	ds_read_b128 v[192:195], v151 offset:51200
	ds_read_b128 v[196:199], v151 offset:52224
	ds_read_b128 v[200:203], v151 offset:53248
	ds_read_b128 v[204:207], v151 offset:54272
	ds_read_b128 v[210:213], v151 offset:55296
	ds_read_b128 v[214:217], v151 offset:56320
	global_load_lds_dwordx4 v[144:145], off
	s_add_i32 m0, s46, 0x2000
	s_add_u32 s4, s4, 0x40080
	v_lshl_add_u64 v[144:145], v[218:219], 0, s[14:15]
	s_addc_u32 s5, s5, 0
	s_add_i32 s46, s67, s81
	global_load_lds_dwordx4 v[144:145], off
	v_lshl_add_u64 v[144:145], s[4:5], 0, v[130:131]
	s_mov_b32 m0, s46
	s_nop 0
	global_load_lds_dwordx4 v[144:145], off
	v_lshl_add_u64 v[144:145], s[4:5], 0, v[134:135]
	s_add_i32 m0, s46, 0x2000
	s_nop 0
	global_load_lds_dwordx4 v[144:145], off
	v_lshl_add_u64 v[144:145], v[220:221], 0, s[14:15]
	s_mov_b32 m0, s49
	s_nop 0
	global_load_lds_dwordx4 v[144:145], off
	v_lshl_add_u64 v[144:145], v[222:223], 0, s[14:15]
	s_mov_b32 m0, s50
	s_nop 0
	global_load_lds_dwordx4 v[144:145], off
	s_waitcnt vmcnt(8) lgkmcnt(0)
	s_barrier
	s_nop 0
	v_mfma_f32_16x16x32_bf16 v[60:63], v[152:155], v[184:187], v[60:63]
	v_mfma_f32_16x16x32_bf16 v[56:59], v[160:163], v[184:187], v[56:59]
	v_mfma_f32_16x16x32_bf16 v[52:55], v[152:155], v[192:195], v[52:55]
	v_mfma_f32_16x16x32_bf16 v[44:47], v[160:163], v[192:195], v[44:47]
	v_mfma_f32_16x16x32_bf16 v[36:39], v[152:155], v[200:203], v[36:39]
	v_mfma_f32_16x16x32_bf16 v[28:31], v[160:163], v[200:203], v[28:31]
	v_mfma_f32_16x16x32_bf16 v[20:23], v[152:155], v[210:213], v[20:23]
	v_mfma_f32_16x16x32_bf16 v[12:15], v[160:163], v[210:213], v[12:15]
	v_mfma_f32_16x16x32_bf16 v[60:63], v[156:159], v[188:191], v[60:63]
	v_mfma_f32_16x16x32_bf16 v[56:59], v[164:167], v[188:191], v[56:59]
	v_mfma_f32_16x16x32_bf16 v[52:55], v[156:159], v[196:199], v[52:55]
	v_mfma_f32_16x16x32_bf16 v[44:47], v[164:167], v[196:199], v[44:47]
	v_mfma_f32_16x16x32_bf16 v[36:39], v[156:159], v[204:207], v[36:39]
	v_mfma_f32_16x16x32_bf16 v[28:31], v[164:167], v[204:207], v[28:31]
	v_mfma_f32_16x16x32_bf16 v[20:23], v[156:159], v[214:217], v[20:23]
	v_mfma_f32_16x16x32_bf16 v[12:15], v[164:167], v[214:217], v[12:15]
	s_nop 0
	s_nop 0
	v_mfma_f32_16x16x32_bf16 v[48:51], v[168:171], v[184:187], v[48:51]
	v_mfma_f32_16x16x32_bf16 v[40:43], v[176:179], v[184:187], v[40:43]
	v_mfma_f32_16x16x32_bf16 v[32:35], v[168:171], v[192:195], v[32:35]
	v_mfma_f32_16x16x32_bf16 v[24:27], v[176:179], v[192:195], v[24:27]
	v_mfma_f32_16x16x32_bf16 v[16:19], v[168:171], v[200:203], v[16:19]
	v_mfma_f32_16x16x32_bf16 v[8:11], v[176:179], v[200:203], v[8:11]
	v_mfma_f32_16x16x32_bf16 v[4:7], v[168:171], v[210:213], v[4:7]
	v_mfma_f32_16x16x32_bf16 v[0:3], v[176:179], v[210:213], v[0:3]
	v_mfma_f32_16x16x32_bf16 v[48:51], v[172:175], v[188:191], v[48:51]
	v_mfma_f32_16x16x32_bf16 v[40:43], v[180:183], v[188:191], v[40:43]
	v_mfma_f32_16x16x32_bf16 v[32:35], v[172:175], v[196:199], v[32:35]
	v_mfma_f32_16x16x32_bf16 v[24:27], v[180:183], v[196:199], v[24:27]
	v_mfma_f32_16x16x32_bf16 v[16:19], v[172:175], v[204:207], v[16:19]
	v_mfma_f32_16x16x32_bf16 v[8:11], v[180:183], v[204:207], v[8:11]
	v_mfma_f32_16x16x32_bf16 v[4:7], v[172:175], v[214:217], v[4:7]
	v_mfma_f32_16x16x32_bf16 v[0:3], v[180:183], v[214:217], v[0:3]
	s_nop 0
	s_barrier
	s_add_i32 s65, s65, 2
	s_add_u32 s44, s44, 0x100
	s_addc_u32 s45, s45, 0
	s_add_u32 s63, s63, 0x100
	s_addc_u32 s64, s64, 0
	s_cmp_gt_u32 s65, 13
	s_cbranch_scc0 .LBB0_125
	s_and_b64 vcc, exec, s[16:17]
	s_cbranch_vccz .LBB0_128
	s_barrier

; #define PG8_STAGE(bufoff, gbase, voff) do { _Pragma("unroll") for (int _i = 0; _i < 2; ++_i) \
;         __builtin_amdgcn_global_load_lds((const unsigned*)((const char*)(gbase) + (voff)[_i]), (LAS unsigned*)(lds + (bufoff) + ldsw + _i * 8192), 16, 0, 0); } while (0)
; #define PG8_LDA(dst, b, h) do { _Pragma("unroll") for (int m = 0; m < 4; ++m) _Pragma("unroll") for (int k = 0; k < 2; ++k) dst[m][k] = *(const LAS bf16x8*)(lds + PG8_SA(b, h) + aoff + m * 2048 + k * 1024); } while (0)
; #define PG8_LDB(dst, b, h) do { _Pragma("unroll") for (int n = 0; n < 2; ++n) _Pragma("unroll") for (int k = 0; k < 2; ++k) dst[n][k] = *(const LAS bf16x8*)(lds + PG8_SB(b, h) + boff + n * 2048 + k * 1024); } while (0)
; #define PG8_MMA(ai, bj, At, Bt) do { __builtin_amdgcn_s_setprio(1); _Pragma("unroll") for (int m = 0; m < 4; ++m) _Pragma("unroll") for (int n = 0; n < 2; ++n) _Pragma("unroll") for (int k = 0; k < 2; ++k) \
;         acc[ai][bj][m][n] = __builtin_amdgcn_mfma_f32_16x16x32_bf16(Bt[n][k], At[m][k], acc[ai][bj][m][n], 0, 0, 0); __builtin_amdgcn_s_setprio(0); } while (0)
; #define PG8_WAIT_V(n) asm volatile("s_waitcnt vmcnt(" #n ")" ::: "memory")
; #define PG8_WAIT_L(n) asm volatile("s_waitcnt lgkmcnt(" #n ")" ::: "memory")
; #define PG8_BAR __builtin_amdgcn_s_barrier()
; #define PG8_SCHED __builtin_amdgcn_sched_barrier(0)
; template <class Epi, class Sched>
; __device__ __forceinline__ void gemm_phase(LAS unsigned char* lds, const Gemm g, const Sched& S, const Epi& E, const int wave_s) {
;     ...
;             const bool last = (t == nt - 2);
;             const char* a1 = cA + (size_t)(t + 1) * kstep;
;             const char* a2 = last ? nA : cA + (size_t)(t + 2) * kstep; const char* b2 = last ? nB : cB + (size_t)(t + 2) * kstep;
;             const char* a3 = a2 + kstep; const char* b3 = b2 + kstep;
;             PG8_LDB(B0, 0, 0); PG8_LDB(B1, 0, 1); PG8_SCHED; PG8_LDA(At, 0, 0); PG8_STAGE(PG8_SA(1, 1), a1 + hstepA, voffA);
;             PG8_WAIT_V(8); PG8_WAIT_L(0); PG8_BAR; PG8_MMA(0, 0, At, B0); PG8_MMA(0, 1, At, B1); PG8_BAR; PG8_SCHED;
;             PG8_LDA(At, 0, 1); PG8_STAGE(PG8_SB(0, 0), b2, voffB); PG8_STAGE(PG8_SB(0, 1), b2 + hstepB, voffB); PG8_STAGE(PG8_SA(0, 0), a2, voffA);
;             PG8_WAIT_V(8); PG8_WAIT_L(0); PG8_BAR; PG8_MMA(1, 0, At, B0); PG8_MMA(1, 1, At, B1); PG8_BAR; PG8_SCHED;
.LBB0_194:
	ds_read_b128 v[144:147], v151
	ds_read_b128 v[154:157], v151 offset:1024
	ds_read_b128 v[158:161], v151 offset:2048
	ds_read_b128 v[162:165], v151 offset:3072
	ds_read_b128 v[166:169], v152
	ds_read_b128 v[170:173], v152 offset:1024
	ds_read_b128 v[174:177], v152 offset:2048
	ds_read_b128 v[178:181], v152 offset:3072
	s_add_u32 s4, s24, 0xfffc0080
	s_addc_u32 s5, s25, -1
	s_cmp_eq_u32 s54, 12
	s_cselect_b32 s27, s19, s5
	s_cselect_b32 s26, s50, s4
	s_cselect_b32 s5, s17, s53
	s_cselect_b32 s4, s51, s52
	v_lshl_add_u64 v[206:207], s[24:25], 0, v[136:137]
	s_add_i32 m0, s30, 0xc000
	ds_read_b128 v[182:185], v153
	ds_read_b128 v[186:189], v153 offset:1024
	ds_read_b128 v[190:193], v153 offset:2048
	ds_read_b128 v[194:197], v153 offset:3072
	ds_read_b128 v[198:201], v153 offset:4096
	ds_read_b128 v[202:205], v153 offset:5120
	ds_read_b128 v[210:213], v153 offset:6144
	ds_read_b128 v[214:217], v153 offset:7168
	global_load_lds_dwordx4 v[206:207], off
	v_lshl_add_u64 v[206:207], s[24:25], 0, v[138:139]
	s_add_i32 m0, s30, 0xe000
	s_nop 0
	global_load_lds_dwordx4 v[206:207], off
	s_waitcnt vmcnt(8) lgkmcnt(0)
	s_barrier
	s_nop 0
	v_mfma_f32_16x16x32_bf16 v[124:127], v[144:147], v[182:185], v[124:127]
	v_mfma_f32_16x16x32_bf16 v[120:123], v[158:161], v[182:185], v[120:123]
	v_mfma_f32_16x16x32_bf16 v[116:119], v[144:147], v[190:193], v[116:119]
	v_mfma_f32_16x16x32_bf16 v[108:111], v[158:161], v[190:193], v[108:111]
	v_mfma_f32_16x16x32_bf16 v[100:103], v[144:147], v[198:201], v[100:103]
	v_mfma_f32_16x16x32_bf16 v[92:95], v[158:161], v[198:201], v[92:95]
	v_mfma_f32_16x16x32_bf16 v[84:87], v[144:147], v[210:213], v[84:87]
	v_mfma_f32_16x16x32_bf16 v[76:79], v[158:161], v[210:213], v[76:79]
	v_mfma_f32_16x16x32_bf16 v[124:127], v[154:157], v[186:189], v[124:127]
	v_mfma_f32_16x16x32_bf16 v[120:123], v[162:165], v[186:189], v[120:123]
	v_mfma_f32_16x16x32_bf16 v[116:119], v[154:157], v[194:197], v[116:119]
	v_mfma_f32_16x16x32_bf16 v[108:111], v[162:165], v[194:197], v[108:111]
	v_mfma_f32_16x16x32_bf16 v[100:103], v[154:157], v[202:205], v[100:103]
	v_mfma_f32_16x16x32_bf16 v[92:95], v[162:165], v[202:205], v[92:95]
	v_mfma_f32_16x16x32_bf16 v[84:87], v[154:157], v[214:217], v[84:87]
	v_mfma_f32_16x16x32_bf16 v[76:79], v[162:165], v[214:217], v[76:79]
	s_nop 0
	s_nop 0
	v_mfma_f32_16x16x32_bf16 v[112:115], v[166:169], v[182:185], v[112:115]
	v_mfma_f32_16x16x32_bf16 v[104:107], v[174:177], v[182:185], v[104:107]
	v_mfma_f32_16x16x32_bf16 v[96:99], v[166:169], v[190:193], v[96:99]
	v_mfma_f32_16x16x32_bf16 v[88:91], v[174:177], v[190:193], v[88:91]
	v_mfma_f32_16x16x32_bf16 v[80:83], v[166:169], v[198:201], v[80:83]
	v_mfma_f32_16x16x32_bf16 v[72:75], v[174:177], v[198:201], v[72:75]
	v_mfma_f32_16x16x32_bf16 v[68:71], v[166:169], v[210:213], v[68:71]
	v_mfma_f32_16x16x32_bf16 v[64:67], v[174:177], v[210:213], v[64:67]
	v_mfma_f32_16x16x32_bf16 v[112:115], v[170:173], v[186:189], v[112:115]
	v_mfma_f32_16x16x32_bf16 v[104:107], v[178:181], v[186:189], v[104:107]
	v_mfma_f32_16x16x32_bf16 v[96:99], v[170:173], v[194:197], v[96:99]
	v_mfma_f32_16x16x32_bf16 v[88:91], v[178:181], v[194:197], v[88:91]
	v_mfma_f32_16x16x32_bf16 v[80:83], v[170:173], v[202:205], v[80:83]
	v_mfma_f32_16x16x32_bf16 v[72:75], v[178:181], v[202:205], v[72:75]
	v_mfma_f32_16x16x32_bf16 v[68:71], v[170:173], v[214:217], v[68:71]
	v_mfma_f32_16x16x32_bf16 v[64:67], v[178:181], v[214:217], v[64:67]
	s_nop 0
	s_barrier
	s_add_i32 s55, s45, s81
	v_lshl_add_u64 v[206:207], s[4:5], 0, v[132:133]
	s_mov_b32 m0, s55
	ds_read_b128 v[182:185], v153 offset:16384
	ds_read_b128 v[186:189], v153 offset:17408
	ds_read_b128 v[190:193], v153 offset:18432
	ds_read_b128 v[194:197], v153 offset:19456
	ds_read_b128 v[198:201], v153 offset:20480
	ds_read_b128 v[202:205], v153 offset:21504
	ds_read_b128 v[210:213], v153 offset:22528
	ds_read_b128 v[214:217], v153 offset:23552
	global_load_lds_dwordx4 v[206:207], off
	s_add_i32 m0, s55, 0x2000
	s_add_u32 s58, s4, 0x40000
	v_lshl_add_u64 v[218:219], s[4:5], 0, v[128:129]
	s_addc_u32 s59, s5, 0
	s_add_i32 s55, s46, s81
	global_load_lds_dwordx4 v[218:219], off
	v_lshl_add_u64 v[220:221], s[58:59], 0, v[132:133]
	s_mov_b32 m0, s55
	v_lshl_add_u64 v[222:223], s[26:27], 0, v[130:131]
	global_load_lds_dwordx4 v[220:221], off
	v_lshl_add_u64 v[220:221], s[58:59], 0, v[128:129]
	s_add_i32 m0, s55, 0x2000
	s_nop 0
	global_load_lds_dwordx4 v[220:221], off
	v_lshl_add_u64 v[220:221], s[26:27], 0, v[134:135]
	s_mov_b32 m0, s30
	s_nop 0
	global_load_lds_dwordx4 v[220:221], off
	s_mov_b32 m0, s31
	s_nop 0
	global_load_lds_dwordx4 v[222:223], off
	s_waitcnt vmcnt(8) lgkmcnt(0)
	s_barrier
; #define PG8_STAGE(bufoff, gbase, voff) do { _Pragma("unroll") for (int _i = 0; _i < 2; ++_i) \
;         __builtin_amdgcn_global_load_lds((const unsigned*)((const char*)(gbase) + (voff)[_i]), (LAS unsigned*)(lds + (bufoff) + ldsw + _i * 8192), 16, 0, 0); } while (0)
; #define PG8_LDA(dst, b, h) do { _Pragma("unroll") for (int m = 0; m < 4; ++m) _Pragma("unroll") for (int k = 0; k < 2; ++k) dst[m][k] = *(const LAS bf16x8*)(lds + PG8_SA(b, h) + aoff + m * 2048 + k * 1024); } while (0)
; #define PG8_LDB(dst, b, h) do { _Pragma("unroll") for (int n = 0; n < 2; ++n) _Pragma("unroll") for (int k = 0; k < 2; ++k) dst[n][k] = *(const LAS bf16x8*)(lds + PG8_SB(b, h) + boff + n * 2048 + k * 1024); } while (0)
; #define PG8_MMA(ai, bj, At, Bt) do { __builtin_amdgcn_s_setprio(1); _Pragma("unroll") for (int m = 0; m < 4; ++m) _Pragma("unroll") for (int n = 0; n < 2; ++n) _Pragma("unroll") for (int k = 0; k < 2; ++k) \
;         acc[ai][bj][m][n] = __builtin_amdgcn_mfma_f32_16x16x32_bf16(Bt[n][k], At[m][k], acc[ai][bj][m][n], 0, 0, 0); __builtin_amdgcn_s_setprio(0); } while (0)
; #define PG8_WAIT_V(n) asm volatile("s_waitcnt vmcnt(" #n ")" ::: "memory")
; #define PG8_WAIT_L(n) asm volatile("s_waitcnt lgkmcnt(" #n ")" ::: "memory")
; #define PG8_BAR __builtin_amdgcn_s_barrier()
; #define PG8_SCHED __builtin_amdgcn_sched_barrier(0)
; template <class Epi, class Sched>
; __device__ __forceinline__ void gemm_phase(LAS unsigned char* lds, const Gemm g, const Sched& S, const Epi& E, const int wave_s) {
;     ...
;             PG8_WAIT_V(8); PG8_WAIT_L(0); PG8_BAR; PG8_MMA(1, 0, At, B0); PG8_MMA(1, 1, At, B1); PG8_BAR; PG8_SCHED;
;             PG8_LDB(B0, 1, 0); PG8_LDB(B1, 1, 1); PG8_SCHED; PG8_LDA(At, 1, 0); PG8_STAGE(PG8_SA(0, 1), a2 + hstepA, voffA);
;             PG8_WAIT_V(8); PG8_WAIT_L(0); PG8_BAR; PG8_MMA(0, 0, At, B0); PG8_MMA(0, 1, At, B1); PG8_BAR; PG8_SCHED;
	s_nop 0
	v_mfma_f32_16x16x32_bf16 v[60:63], v[144:147], v[182:185], v[60:63]
	v_mfma_f32_16x16x32_bf16 v[56:59], v[158:161], v[182:185], v[56:59]
	v_mfma_f32_16x16x32_bf16 v[52:55], v[144:147], v[190:193], v[52:55]
	v_mfma_f32_16x16x32_bf16 v[44:47], v[158:161], v[190:193], v[44:47]
	v_mfma_f32_16x16x32_bf16 v[36:39], v[144:147], v[198:201], v[36:39]
	v_mfma_f32_16x16x32_bf16 v[28:31], v[158:161], v[198:201], v[28:31]
	v_mfma_f32_16x16x32_bf16 v[20:23], v[144:147], v[210:213], v[20:23]
	v_mfma_f32_16x16x32_bf16 v[12:15], v[158:161], v[210:213], v[12:15]
	v_mfma_f32_16x16x32_bf16 v[60:63], v[154:157], v[186:189], v[60:63]
	v_mfma_f32_16x16x32_bf16 v[56:59], v[162:165], v[186:189], v[56:59]
	v_mfma_f32_16x16x32_bf16 v[52:55], v[154:157], v[194:197], v[52:55]
	v_mfma_f32_16x16x32_bf16 v[44:47], v[162:165], v[194:197], v[44:47]
	v_mfma_f32_16x16x32_bf16 v[36:39], v[154:157], v[202:205], v[36:39]
	v_mfma_f32_16x16x32_bf16 v[28:31], v[162:165], v[202:205], v[28:31]
	v_mfma_f32_16x16x32_bf16 v[20:23], v[154:157], v[214:217], v[20:23]
	v_mfma_f32_16x16x32_bf16 v[12:15], v[162:165], v[214:217], v[12:15]
	s_nop 0
	s_nop 0
	v_mfma_f32_16x16x32_bf16 v[48:51], v[166:169], v[182:185], v[48:51]
	v_mfma_f32_16x16x32_bf16 v[40:43], v[174:177], v[182:185], v[40:43]
	v_mfma_f32_16x16x32_bf16 v[32:35], v[166:169], v[190:193], v[32:35]
	v_mfma_f32_16x16x32_bf16 v[24:27], v[174:177], v[190:193], v[24:27]
	v_mfma_f32_16x16x32_bf16 v[16:19], v[166:169], v[198:201], v[16:19]
	v_mfma_f32_16x16x32_bf16 v[8:11], v[174:177], v[198:201], v[8:11]
	v_mfma_f32_16x16x32_bf16 v[4:7], v[166:169], v[210:213], v[4:7]
	v_mfma_f32_16x16x32_bf16 v[0:3], v[174:177], v[210:213], v[0:3]
	v_mfma_f32_16x16x32_bf16 v[48:51], v[170:173], v[186:189], v[48:51]
	v_mfma_f32_16x16x32_bf16 v[40:43], v[178:181], v[186:189], v[40:43]
	v_mfma_f32_16x16x32_bf16 v[32:35], v[170:173], v[194:197], v[32:35]
	v_mfma_f32_16x16x32_bf16 v[24:27], v[178:181], v[194:197], v[24:27]
	v_mfma_f32_16x16x32_bf16 v[16:19], v[170:173], v[202:205], v[16:19]
	v_mfma_f32_16x16x32_bf16 v[8:11], v[178:181], v[202:205], v[8:11]
	v_mfma_f32_16x16x32_bf16 v[4:7], v[170:173], v[214:217], v[4:7]
	v_mfma_f32_16x16x32_bf16 v[0:3], v[178:181], v[214:217], v[0:3]
	s_nop 0
	s_barrier
	s_add_i32 s55, 0, 0x18000
	s_add_i32 s57, 0, 0x1c000
	v_add_u32_e32 v162, s55, v149
	v_add_u32_e32 v178, s57, v149
	ds_read_b128 v[144:147], v162
	ds_read_b128 v[154:157], v162 offset:1024
	ds_read_b128 v[158:161], v162 offset:2048
	ds_read_b128 v[162:165], v162 offset:3072
	ds_read_b128 v[166:169], v178
	ds_read_b128 v[170:173], v178 offset:1024
	ds_read_b128 v[174:177], v178 offset:2048
	ds_read_b128 v[178:181], v178 offset:3072
	s_add_u32 s26, s26, 0x40000
	s_addc_u32 s27, s27, 0
	s_mov_b32 m0, s33
	v_lshl_add_u64 v[224:225], s[26:27], 0, v[134:135]
	ds_read_b128 v[182:185], v153 offset:32768
	ds_read_b128 v[186:189], v153 offset:33792
	ds_read_b128 v[190:193], v153 offset:34816
	ds_read_b128 v[194:197], v153 offset:35840
	ds_read_b128 v[198:201], v153 offset:36864
	ds_read_b128 v[202:205], v153 offset:37888
	ds_read_b128 v[210:213], v153 offset:38912
	ds_read_b128 v[214:217], v153 offset:39936
	global_load_lds_dwordx4 v[224:225], off
	v_lshl_add_u64 v[224:225], s[26:27], 0, v[130:131]
	s_mov_b32 m0, s35
	s_nop 0
	global_load_lds_dwordx4 v[224:225], off
	s_waitcnt vmcnt(8) lgkmcnt(0)
	s_barrier
	s_nop 0
	v_mfma_f32_16x16x32_bf16 v[124:127], v[144:147], v[182:185], v[124:127]
	v_mfma_f32_16x16x32_bf16 v[120:123], v[158:161], v[182:185], v[120:123]
	v_mfma_f32_16x16x32_bf16 v[116:119], v[144:147], v[190:193], v[116:119]
	v_mfma_f32_16x16x32_bf16 v[108:111], v[158:161], v[190:193], v[108:111]
	v_mfma_f32_16x16x32_bf16 v[100:103], v[144:147], v[198:201], v[100:103]
	v_mfma_f32_16x16x32_bf16 v[92:95], v[158:161], v[198:201], v[92:95]
	v_mfma_f32_16x16x32_bf16 v[84:87], v[144:147], v[210:213], v[84:87]
	v_mfma_f32_16x16x32_bf16 v[76:79], v[158:161], v[210:213], v[76:79]
	v_mfma_f32_16x16x32_bf16 v[124:127], v[154:157], v[186:189], v[124:127]
	v_mfma_f32_16x16x32_bf16 v[120:123], v[162:165], v[186:189], v[120:123]
	v_mfma_f32_16x16x32_bf16 v[116:119], v[154:157], v[194:197], v[116:119]
	v_mfma_f32_16x16x32_bf16 v[108:111], v[162:165], v[194:197], v[108:111]
	v_mfma_f32_16x16x32_bf16 v[100:103], v[154:157], v[202:205], v[100:103]
	v_mfma_f32_16x16x32_bf16 v[92:95], v[162:165], v[202:205], v[92:95]
	v_mfma_f32_16x16x32_bf16 v[84:87], v[154:157], v[214:217], v[84:87]
	v_mfma_f32_16x16x32_bf16 v[76:79], v[162:165], v[214:217], v[76:79]
	s_nop 0
	s_nop 0
	v_mfma_f32_16x16x32_bf16 v[112:115], v[166:169], v[182:185], v[112:115]
	v_mfma_f32_16x16x32_bf16 v[104:107], v[174:177], v[182:185], v[104:107]
	v_mfma_f32_16x16x32_bf16 v[96:99], v[166:169], v[190:193], v[96:99]
	v_mfma_f32_16x16x32_bf16 v[88:91], v[174:177], v[190:193], v[88:91]
	v_mfma_f32_16x16x32_bf16 v[80:83], v[166:169], v[198:201], v[80:83]
	v_mfma_f32_16x16x32_bf16 v[72:75], v[174:177], v[198:201], v[72:75]
	v_mfma_f32_16x16x32_bf16 v[68:71], v[166:169], v[210:213], v[68:71]
	v_mfma_f32_16x16x32_bf16 v[64:67], v[174:177], v[210:213], v[64:67]
	v_mfma_f32_16x16x32_bf16 v[112:115], v[170:173], v[186:189], v[112:115]
	v_mfma_f32_16x16x32_bf16 v[104:107], v[178:181], v[186:189], v[104:107]
	v_mfma_f32_16x16x32_bf16 v[96:99], v[170:173], v[194:197], v[96:99]
	v_mfma_f32_16x16x32_bf16 v[88:91], v[178:181], v[194:197], v[88:91]
	v_mfma_f32_16x16x32_bf16 v[80:83], v[170:173], v[202:205], v[80:83]
	v_mfma_f32_16x16x32_bf16 v[72:75], v[178:181], v[202:205], v[72:75]
	v_mfma_f32_16x16x32_bf16 v[68:71], v[170:173], v[214:217], v[68:71]
	v_mfma_f32_16x16x32_bf16 v[64:67], v[178:181], v[214:217], v[64:67]
	s_nop 0
	s_barrier
; #define PG8_STAGE(bufoff, gbase, voff) do { _Pragma("unroll") for (int _i = 0; _i < 2; ++_i) \
;         __builtin_amdgcn_global_load_lds((const unsigned*)((const char*)(gbase) + (voff)[_i]), (LAS unsigned*)(lds + (bufoff) + ldsw + _i * 8192), 16, 0, 0); } while (0)
; #define PG8_LDA(dst, b, h) do { _Pragma("unroll") for (int m = 0; m < 4; ++m) _Pragma("unroll") for (int k = 0; k < 2; ++k) dst[m][k] = *(const LAS bf16x8*)(lds + PG8_SA(b, h) + aoff + m * 2048 + k * 1024); } while (0)
; #define PG8_MMA(ai, bj, At, Bt) do { __builtin_amdgcn_s_setprio(1); _Pragma("unroll") for (int m = 0; m < 4; ++m) _Pragma("unroll") for (int n = 0; n < 2; ++n) _Pragma("unroll") for (int k = 0; k < 2; ++k) \
;         acc[ai][bj][m][n] = __builtin_amdgcn_mfma_f32_16x16x32_bf16(Bt[n][k], At[m][k], acc[ai][bj][m][n], 0, 0, 0); __builtin_amdgcn_s_setprio(0); } while (0)
; #define PG8_WAIT_V(n) asm volatile("s_waitcnt vmcnt(" #n ")" ::: "memory")
; #define PG8_WAIT_L(n) asm volatile("s_waitcnt lgkmcnt(" #n ")" ::: "memory")
; #define PG8_BAR __builtin_amdgcn_s_barrier()
; #define PG8_SCHED __builtin_amdgcn_sched_barrier(0)
; template <class Epi, class Sched>
; __device__ __forceinline__ void gemm_phase(LAS unsigned char* lds, const Gemm g, const Sched& S, const Epi& E, const int wave_s) {
;     ...
;             PG8_LDA(At, 1, 1); PG8_STAGE(PG8_SB(1, 0), b3, voffB); PG8_STAGE(PG8_SB(1, 1), b3 + hstepB, voffB); PG8_STAGE(PG8_SA(1, 0), a3, voffA);
;             PG8_WAIT_V(8); PG8_WAIT_L(0); PG8_BAR; PG8_MMA(1, 0, At, B0); PG8_MMA(1, 1, At, B1); PG8_BAR; PG8_SCHED;
;         }
	s_add_i32 s26, s55, s81
	v_lshl_add_u64 v[206:207], v[206:207], 0, s[12:13]
	s_mov_b32 m0, s26
	ds_read_b128 v[182:185], v153 offset:49152
	ds_read_b128 v[186:189], v153 offset:50176
	ds_read_b128 v[190:193], v153 offset:51200
	ds_read_b128 v[194:197], v153 offset:52224
	ds_read_b128 v[198:201], v153 offset:53248
	ds_read_b128 v[202:205], v153 offset:54272
	ds_read_b128 v[210:213], v153 offset:55296
	ds_read_b128 v[214:217], v153 offset:56320
	global_load_lds_dwordx4 v[206:207], off
	s_add_i32 m0, s26, 0x2000
	s_add_u32 s4, s4, 0x40080
	v_lshl_add_u64 v[206:207], v[218:219], 0, s[12:13]
	s_addc_u32 s5, s5, 0
	s_add_i32 s26, s57, s81
	global_load_lds_dwordx4 v[206:207], off
	v_lshl_add_u64 v[206:207], s[4:5], 0, v[132:133]
	s_mov_b32 m0, s26
	s_nop 0
	global_load_lds_dwordx4 v[206:207], off
	v_lshl_add_u64 v[206:207], s[4:5], 0, v[128:129]
	s_add_i32 m0, s26, 0x2000
	s_nop 0
	global_load_lds_dwordx4 v[206:207], off
	v_lshl_add_u64 v[206:207], v[220:221], 0, s[12:13]
	s_mov_b32 m0, s41
	s_nop 0
	global_load_lds_dwordx4 v[206:207], off
	v_lshl_add_u64 v[206:207], v[222:223], 0, s[12:13]
	s_mov_b32 m0, s42
	s_nop 0
	global_load_lds_dwordx4 v[206:207], off
	s_waitcnt vmcnt(8) lgkmcnt(0)
	s_barrier
	s_nop 0
	v_mfma_f32_16x16x32_bf16 v[60:63], v[144:147], v[182:185], v[60:63]
	v_mfma_f32_16x16x32_bf16 v[56:59], v[158:161], v[182:185], v[56:59]
	v_mfma_f32_16x16x32_bf16 v[52:55], v[144:147], v[190:193], v[52:55]
	v_mfma_f32_16x16x32_bf16 v[44:47], v[158:161], v[190:193], v[44:47]
	v_mfma_f32_16x16x32_bf16 v[36:39], v[144:147], v[198:201], v[36:39]
	v_mfma_f32_16x16x32_bf16 v[28:31], v[158:161], v[198:201], v[28:31]
	v_mfma_f32_16x16x32_bf16 v[20:23], v[144:147], v[210:213], v[20:23]
	v_mfma_f32_16x16x32_bf16 v[12:15], v[158:161], v[210:213], v[12:15]
	v_mfma_f32_16x16x32_bf16 v[60:63], v[154:157], v[186:189], v[60:63]
	v_mfma_f32_16x16x32_bf16 v[56:59], v[162:165], v[186:189], v[56:59]
	v_mfma_f32_16x16x32_bf16 v[52:55], v[154:157], v[194:197], v[52:55]
	v_mfma_f32_16x16x32_bf16 v[44:47], v[162:165], v[194:197], v[44:47]
	v_mfma_f32_16x16x32_bf16 v[36:39], v[154:157], v[202:205], v[36:39]
	v_mfma_f32_16x16x32_bf16 v[28:31], v[162:165], v[202:205], v[28:31]
	v_mfma_f32_16x16x32_bf16 v[20:23], v[154:157], v[214:217], v[20:23]
	v_mfma_f32_16x16x32_bf16 v[12:15], v[162:165], v[214:217], v[12:15]
	s_nop 0
	s_nop 0
	v_mfma_f32_16x16x32_bf16 v[48:51], v[166:169], v[182:185], v[48:51]
	v_mfma_f32_16x16x32_bf16 v[40:43], v[174:177], v[182:185], v[40:43]
	v_mfma_f32_16x16x32_bf16 v[32:35], v[166:169], v[190:193], v[32:35]
	v_mfma_f32_16x16x32_bf16 v[24:27], v[174:177], v[190:193], v[24:27]
	v_mfma_f32_16x16x32_bf16 v[16:19], v[166:169], v[198:201], v[16:19]
	v_mfma_f32_16x16x32_bf16 v[8:11], v[174:177], v[198:201], v[8:11]
	v_mfma_f32_16x16x32_bf16 v[4:7], v[166:169], v[210:213], v[4:7]
	v_mfma_f32_16x16x32_bf16 v[0:3], v[174:177], v[210:213], v[0:3]
	v_mfma_f32_16x16x32_bf16 v[48:51], v[170:173], v[186:189], v[48:51]
	v_mfma_f32_16x16x32_bf16 v[40:43], v[178:181], v[186:189], v[40:43]
	v_mfma_f32_16x16x32_bf16 v[32:35], v[170:173], v[194:197], v[32:35]
	v_mfma_f32_16x16x32_bf16 v[24:27], v[178:181], v[194:197], v[24:27]
	v_mfma_f32_16x16x32_bf16 v[16:19], v[170:173], v[202:205], v[16:19]
	v_mfma_f32_16x16x32_bf16 v[8:11], v[178:181], v[202:205], v[8:11]
	v_mfma_f32_16x16x32_bf16 v[4:7], v[170:173], v[214:217], v[4:7]
	v_mfma_f32_16x16x32_bf16 v[0:3], v[178:181], v[214:217], v[0:3]
	s_nop 0
	s_barrier
	s_add_i32 s54, s54, 2
	s_add_u32 s24, s24, 0x100
	s_addc_u32 s25, s25, 0
	s_add_u32 s52, s52, 0x100
	s_addc_u32 s53, s53, 0
	s_cmp_gt_u32 s54, 13
	s_cbranch_scc0 .LBB0_194
	s_and_b64 vcc, exec, s[14:15]
	s_cbranch_vccz .LBB0_197
	s_barrier

; #define PG8_STAGE(bufoff, gbase, voff) do { _Pragma("unroll") for (int _i = 0; _i < 2; ++_i) \
;         __builtin_amdgcn_global_load_lds((const unsigned*)((const char*)(gbase) + (voff)[_i]), (LAS unsigned*)(lds + (bufoff) + ldsw + _i * 8192), 16, 0, 0); } while (0)
; #define PG8_LDA(dst, b, h) do { _Pragma("unroll") for (int m = 0; m < 4; ++m) _Pragma("unroll") for (int k = 0; k < 2; ++k) dst[m][k] = *(const LAS bf16x8*)(lds + PG8_SA(b, h) + aoff + m * 2048 + k * 1024); } while (0)
; #define PG8_LDB(dst, b, h) do { _Pragma("unroll") for (int n = 0; n < 2; ++n) _Pragma("unroll") for (int k = 0; k < 2; ++k) dst[n][k] = *(const LAS bf16x8*)(lds + PG8_SB(b, h) + boff + n * 2048 + k * 1024); } while (0)
; #define PG8_MMA(ai, bj, At, Bt) do { __builtin_amdgcn_s_setprio(1); _Pragma("unroll") for (int m = 0; m < 4; ++m) _Pragma("unroll") for (int n = 0; n < 2; ++n) _Pragma("unroll") for (int k = 0; k < 2; ++k) \
;         acc[ai][bj][m][n] = __builtin_amdgcn_mfma_f32_16x16x32_bf16(Bt[n][k], At[m][k], acc[ai][bj][m][n], 0, 0, 0); __builtin_amdgcn_s_setprio(0); } while (0)
; #define PG8_WAIT_V(n) asm volatile("s_waitcnt vmcnt(" #n ")" ::: "memory")
; #define PG8_WAIT_L(n) asm volatile("s_waitcnt lgkmcnt(" #n ")" ::: "memory")
; #define PG8_BAR __builtin_amdgcn_s_barrier()
; #define PG8_SCHED __builtin_amdgcn_sched_barrier(0)
; template <class Epi, class Sched>
; __device__ __forceinline__ void gemm_phase(LAS unsigned char* lds, const Gemm g, const Sched& S, const Epi& E, const int wave_s) {
;     ...
;             const bool last = (t == nt - 2);
;             const char* a1 = cA + (size_t)(t + 1) * kstep;
;             const char* a2 = last ? nA : cA + (size_t)(t + 2) * kstep; const char* b2 = last ? nB : cB + (size_t)(t + 2) * kstep;
;             const char* a3 = a2 + kstep; const char* b3 = b2 + kstep;
;             PG8_LDB(B0, 0, 0); PG8_LDB(B1, 0, 1); PG8_SCHED; PG8_LDA(At, 0, 0); PG8_STAGE(PG8_SA(1, 1), a1 + hstepA, voffA);
;             PG8_WAIT_V(8); PG8_WAIT_L(0); PG8_BAR; PG8_MMA(0, 0, At, B0); PG8_MMA(0, 1, At, B1); PG8_BAR; PG8_SCHED;
;             PG8_LDA(At, 0, 1); PG8_STAGE(PG8_SB(0, 0), b2, voffB); PG8_STAGE(PG8_SB(0, 1), b2 + hstepB, voffB); PG8_STAGE(PG8_SA(0, 0), a2, voffA);
;             PG8_WAIT_V(8); PG8_WAIT_L(0); PG8_BAR; PG8_MMA(1, 0, At, B0); PG8_MMA(1, 1, At, B1); PG8_BAR; PG8_SCHED;
.LBB0_375:
	ds_read_b128 v[158:161], v155
	ds_read_b128 v[162:165], v155 offset:1024
	ds_read_b128 v[166:169], v155 offset:2048
	ds_read_b128 v[170:173], v155 offset:3072
	ds_read_b128 v[174:177], v156
	ds_read_b128 v[178:181], v156 offset:1024
	ds_read_b128 v[182:185], v156 offset:2048
	ds_read_b128 v[186:189], v156 offset:3072
	s_add_u32 s4, s22, 0x100
	s_addc_u32 s5, s23, 0
	s_cmp_eq_u32 s48, 2
	s_cselect_b32 s25, s19, s5
	s_cselect_b32 s24, s18, s4
	s_cselect_b32 s9, s21, s47
	s_cselect_b32 s8, s20, s46
	v_lshl_add_u64 v[150:151], s[22:23], 0, v[142:143]
	s_add_i32 m0, s27, 0xc000
	ds_read_b128 v[190:193], v157
	ds_read_b128 v[194:197], v157 offset:1024
	ds_read_b128 v[198:201], v157 offset:2048
	ds_read_b128 v[202:205], v157 offset:3072
	ds_read_b128 v[210:213], v157 offset:4096
	ds_read_b128 v[214:217], v157 offset:5120
	ds_read_b128 v[218:221], v157 offset:6144
	ds_read_b128 v[222:225], v157 offset:7168
	global_load_lds_dwordx4 v[150:151], off
	v_lshl_add_u64 v[150:151], s[22:23], 0, v[144:145]
	s_add_i32 m0, s27, 0xe000
	s_nop 0
	global_load_lds_dwordx4 v[150:151], off
	s_waitcnt vmcnt(8) lgkmcnt(0)
	s_barrier
	s_nop 0
	v_mfma_f32_16x16x32_bf16 v[124:127], v[158:161], v[190:193], v[124:127]
	v_mfma_f32_16x16x32_bf16 v[120:123], v[166:169], v[190:193], v[120:123]
	v_mfma_f32_16x16x32_bf16 v[108:111], v[158:161], v[198:201], v[108:111]
	v_mfma_f32_16x16x32_bf16 v[104:107], v[166:169], v[198:201], v[104:107]
	v_mfma_f32_16x16x32_bf16 v[92:95], v[158:161], v[210:213], v[92:95]
	v_mfma_f32_16x16x32_bf16 v[88:91], v[166:169], v[210:213], v[88:91]
	v_mfma_f32_16x16x32_bf16 v[76:79], v[158:161], v[218:221], v[76:79]
	v_mfma_f32_16x16x32_bf16 v[72:75], v[166:169], v[218:221], v[72:75]
	v_mfma_f32_16x16x32_bf16 v[124:127], v[162:165], v[194:197], v[124:127]
	v_mfma_f32_16x16x32_bf16 v[120:123], v[170:173], v[194:197], v[120:123]
	v_mfma_f32_16x16x32_bf16 v[108:111], v[162:165], v[202:205], v[108:111]
	v_mfma_f32_16x16x32_bf16 v[104:107], v[170:173], v[202:205], v[104:107]
	v_mfma_f32_16x16x32_bf16 v[92:95], v[162:165], v[214:217], v[92:95]
	v_mfma_f32_16x16x32_bf16 v[88:91], v[170:173], v[214:217], v[88:91]
	v_mfma_f32_16x16x32_bf16 v[76:79], v[162:165], v[222:225], v[76:79]
	v_mfma_f32_16x16x32_bf16 v[72:75], v[170:173], v[222:225], v[72:75]
	s_nop 0
	s_nop 0
	v_mfma_f32_16x16x32_bf16 v[116:119], v[174:177], v[190:193], v[116:119]
	v_mfma_f32_16x16x32_bf16 v[112:115], v[182:185], v[190:193], v[112:115]
	v_mfma_f32_16x16x32_bf16 v[100:103], v[174:177], v[198:201], v[100:103]
	v_mfma_f32_16x16x32_bf16 v[96:99], v[182:185], v[198:201], v[96:99]
	v_mfma_f32_16x16x32_bf16 v[84:87], v[174:177], v[210:213], v[84:87]
	v_mfma_f32_16x16x32_bf16 v[80:83], v[182:185], v[210:213], v[80:83]
	v_mfma_f32_16x16x32_bf16 v[68:71], v[174:177], v[218:221], v[68:71]
	v_mfma_f32_16x16x32_bf16 v[64:67], v[182:185], v[218:221], v[64:67]
	v_mfma_f32_16x16x32_bf16 v[116:119], v[178:181], v[194:197], v[116:119]
	v_mfma_f32_16x16x32_bf16 v[112:115], v[186:189], v[194:197], v[112:115]
	v_mfma_f32_16x16x32_bf16 v[100:103], v[178:181], v[202:205], v[100:103]
	v_mfma_f32_16x16x32_bf16 v[96:99], v[186:189], v[202:205], v[96:99]
	v_mfma_f32_16x16x32_bf16 v[84:87], v[178:181], v[214:217], v[84:87]
	v_mfma_f32_16x16x32_bf16 v[80:83], v[186:189], v[214:217], v[80:83]
	v_mfma_f32_16x16x32_bf16 v[68:71], v[178:181], v[222:225], v[68:71]
	v_mfma_f32_16x16x32_bf16 v[64:67], v[186:189], v[222:225], v[64:67]
	s_nop 0
	s_barrier
	s_add_i32 s22, s39, s81
	v_lshl_add_u64 v[150:151], s[8:9], 0, v[130:131]
	s_mov_b32 m0, s22
	ds_read_b128 v[190:193], v157 offset:16384
	ds_read_b128 v[194:197], v157 offset:17408
	ds_read_b128 v[198:201], v157 offset:18432
	ds_read_b128 v[202:205], v157 offset:19456
	ds_read_b128 v[210:213], v157 offset:20480
	ds_read_b128 v[214:217], v157 offset:21504
	ds_read_b128 v[218:221], v157 offset:22528
	ds_read_b128 v[222:225], v157 offset:23552
	global_load_lds_dwordx4 v[150:151], off
	s_add_i32 m0, s22, 0x2000
	s_add_u32 s22, s8, 0x18000
	v_lshl_add_u64 v[206:207], s[8:9], 0, v[134:135]
	s_addc_u32 s23, s9, 0
	s_add_i32 s49, s40, s81
	global_load_lds_dwordx4 v[206:207], off
	v_lshl_add_u64 v[226:227], s[22:23], 0, v[130:131]
	s_mov_b32 m0, s49
	v_lshl_add_u64 v[228:229], s[24:25], 0, v[132:133]
	global_load_lds_dwordx4 v[226:227], off
	v_lshl_add_u64 v[226:227], s[22:23], 0, v[134:135]
	s_add_i32 m0, s49, 0x2000
	s_nop 0
	global_load_lds_dwordx4 v[226:227], off
	v_lshl_add_u64 v[226:227], s[24:25], 0, v[128:129]
	s_mov_b32 m0, s27
	s_nop 0
	global_load_lds_dwordx4 v[226:227], off
	s_mov_b32 m0, s28
	s_nop 0
	global_load_lds_dwordx4 v[228:229], off
	s_waitcnt vmcnt(8) lgkmcnt(0)
	s_barrier
; #define PG8_STAGE(bufoff, gbase, voff) do { _Pragma("unroll") for (int _i = 0; _i < 2; ++_i) \
;         __builtin_amdgcn_global_load_lds((const unsigned*)((const char*)(gbase) + (voff)[_i]), (LAS unsigned*)(lds + (bufoff) + ldsw + _i * 8192), 16, 0, 0); } while (0)
; #define PG8_LDA(dst, b, h) do { _Pragma("unroll") for (int m = 0; m < 4; ++m) _Pragma("unroll") for (int k = 0; k < 2; ++k) dst[m][k] = *(const LAS bf16x8*)(lds + PG8_SA(b, h) + aoff + m * 2048 + k * 1024); } while (0)
; #define PG8_LDB(dst, b, h) do { _Pragma("unroll") for (int n = 0; n < 2; ++n) _Pragma("unroll") for (int k = 0; k < 2; ++k) dst[n][k] = *(const LAS bf16x8*)(lds + PG8_SB(b, h) + boff + n * 2048 + k * 1024); } while (0)
; #define PG8_MMA(ai, bj, At, Bt) do { __builtin_amdgcn_s_setprio(1); _Pragma("unroll") for (int m = 0; m < 4; ++m) _Pragma("unroll") for (int n = 0; n < 2; ++n) _Pragma("unroll") for (int k = 0; k < 2; ++k) \
;         acc[ai][bj][m][n] = __builtin_amdgcn_mfma_f32_16x16x32_bf16(Bt[n][k], At[m][k], acc[ai][bj][m][n], 0, 0, 0); __builtin_amdgcn_s_setprio(0); } while (0)
; #define PG8_WAIT_V(n) asm volatile("s_waitcnt vmcnt(" #n ")" ::: "memory")
; #define PG8_WAIT_L(n) asm volatile("s_waitcnt lgkmcnt(" #n ")" ::: "memory")
; #define PG8_BAR __builtin_amdgcn_s_barrier()
; #define PG8_SCHED __builtin_amdgcn_sched_barrier(0)
; template <class Epi, class Sched>
; __device__ __forceinline__ void gemm_phase(LAS unsigned char* lds, const Gemm g, const Sched& S, const Epi& E, const int wave_s) {
;     ...
;             PG8_WAIT_V(8); PG8_WAIT_L(0); PG8_BAR; PG8_MMA(1, 0, At, B0); PG8_MMA(1, 1, At, B1); PG8_BAR; PG8_SCHED;
;             PG8_LDB(B0, 1, 0); PG8_LDB(B1, 1, 1); PG8_SCHED; PG8_LDA(At, 1, 0); PG8_STAGE(PG8_SA(0, 1), a2 + hstepA, voffA);
;             PG8_WAIT_V(8); PG8_WAIT_L(0); PG8_BAR; PG8_MMA(0, 0, At, B0); PG8_MMA(0, 1, At, B1); PG8_BAR; PG8_SCHED;
	s_nop 0
	v_mfma_f32_16x16x32_bf16 v[60:63], v[158:161], v[190:193], v[60:63]
	v_mfma_f32_16x16x32_bf16 v[56:59], v[166:169], v[190:193], v[56:59]
	v_mfma_f32_16x16x32_bf16 v[44:47], v[158:161], v[198:201], v[44:47]
	v_mfma_f32_16x16x32_bf16 v[40:43], v[166:169], v[198:201], v[40:43]
	v_mfma_f32_16x16x32_bf16 v[28:31], v[158:161], v[210:213], v[28:31]
	v_mfma_f32_16x16x32_bf16 v[24:27], v[166:169], v[210:213], v[24:27]
	v_mfma_f32_16x16x32_bf16 v[12:15], v[158:161], v[218:221], v[12:15]
	v_mfma_f32_16x16x32_bf16 v[8:11], v[166:169], v[218:221], v[8:11]
	v_mfma_f32_16x16x32_bf16 v[60:63], v[162:165], v[194:197], v[60:63]
	v_mfma_f32_16x16x32_bf16 v[56:59], v[170:173], v[194:197], v[56:59]
	v_mfma_f32_16x16x32_bf16 v[44:47], v[162:165], v[202:205], v[44:47]
	v_mfma_f32_16x16x32_bf16 v[40:43], v[170:173], v[202:205], v[40:43]
	v_mfma_f32_16x16x32_bf16 v[28:31], v[162:165], v[214:217], v[28:31]
	v_mfma_f32_16x16x32_bf16 v[24:27], v[170:173], v[214:217], v[24:27]
	v_mfma_f32_16x16x32_bf16 v[12:15], v[162:165], v[222:225], v[12:15]
	v_mfma_f32_16x16x32_bf16 v[8:11], v[170:173], v[222:225], v[8:11]
	s_nop 0
	s_nop 0
	v_mfma_f32_16x16x32_bf16 v[52:55], v[174:177], v[190:193], v[52:55]
	v_mfma_f32_16x16x32_bf16 v[48:51], v[182:185], v[190:193], v[48:51]
	v_mfma_f32_16x16x32_bf16 v[36:39], v[174:177], v[198:201], v[36:39]
	v_mfma_f32_16x16x32_bf16 v[32:35], v[182:185], v[198:201], v[32:35]
	v_mfma_f32_16x16x32_bf16 v[20:23], v[174:177], v[210:213], v[20:23]
	v_mfma_f32_16x16x32_bf16 v[16:19], v[182:185], v[210:213], v[16:19]
	v_mfma_f32_16x16x32_bf16 v[4:7], v[174:177], v[218:221], v[4:7]
	v_mfma_f32_16x16x32_bf16 v[0:3], v[182:185], v[218:221], v[0:3]
	v_mfma_f32_16x16x32_bf16 v[52:55], v[178:181], v[194:197], v[52:55]
	v_mfma_f32_16x16x32_bf16 v[48:51], v[186:189], v[194:197], v[48:51]
	v_mfma_f32_16x16x32_bf16 v[36:39], v[178:181], v[202:205], v[36:39]
	v_mfma_f32_16x16x32_bf16 v[32:35], v[186:189], v[202:205], v[32:35]
	v_mfma_f32_16x16x32_bf16 v[20:23], v[178:181], v[214:217], v[20:23]
	v_mfma_f32_16x16x32_bf16 v[16:19], v[186:189], v[214:217], v[16:19]
	v_mfma_f32_16x16x32_bf16 v[4:7], v[178:181], v[222:225], v[4:7]
	v_mfma_f32_16x16x32_bf16 v[0:3], v[186:189], v[222:225], v[0:3]
	s_nop 0
	s_barrier
	s_add_i32 s49, 0, 0x18000
	v_add_u32_e32 v136, s49, v153
	s_add_i32 s50, 0, 0x1c000
	ds_read_b128 v[158:161], v136
	ds_read_b128 v[162:165], v136 offset:1024
	ds_read_b128 v[166:169], v136 offset:2048
	ds_read_b128 v[170:173], v136 offset:3072
	v_add_u32_e32 v136, s50, v153
	ds_read_b128 v[174:177], v136
	ds_read_b128 v[178:181], v136 offset:1024
	ds_read_b128 v[182:185], v136 offset:2048
	ds_read_b128 v[186:189], v136 offset:3072
	s_add_u32 s22, s24, 0xf0000
	s_addc_u32 s23, s25, 0
	s_mov_b32 m0, s29
	v_lshl_add_u64 v[230:231], s[22:23], 0, v[128:129]
	ds_read_b128 v[190:193], v157 offset:32768
	ds_read_b128 v[194:197], v157 offset:33792
	ds_read_b128 v[198:201], v157 offset:34816
	ds_read_b128 v[202:205], v157 offset:35840
	ds_read_b128 v[210:213], v157 offset:36864
	ds_read_b128 v[214:217], v157 offset:37888
	ds_read_b128 v[218:221], v157 offset:38912
	ds_read_b128 v[222:225], v157 offset:39936
	global_load_lds_dwordx4 v[230:231], off
	v_lshl_add_u64 v[230:231], s[22:23], 0, v[132:133]
	s_mov_b32 m0, s30
	s_nop 0
	global_load_lds_dwordx4 v[230:231], off
	s_waitcnt vmcnt(8) lgkmcnt(0)
	s_barrier
	s_nop 0
	v_mfma_f32_16x16x32_bf16 v[124:127], v[158:161], v[190:193], v[124:127]
	v_mfma_f32_16x16x32_bf16 v[120:123], v[166:169], v[190:193], v[120:123]
	v_mfma_f32_16x16x32_bf16 v[108:111], v[158:161], v[198:201], v[108:111]
	v_mfma_f32_16x16x32_bf16 v[104:107], v[166:169], v[198:201], v[104:107]
	v_mfma_f32_16x16x32_bf16 v[92:95], v[158:161], v[210:213], v[92:95]
	v_mfma_f32_16x16x32_bf16 v[88:91], v[166:169], v[210:213], v[88:91]
	v_mfma_f32_16x16x32_bf16 v[76:79], v[158:161], v[218:221], v[76:79]
	v_mfma_f32_16x16x32_bf16 v[72:75], v[166:169], v[218:221], v[72:75]
	v_mfma_f32_16x16x32_bf16 v[124:127], v[162:165], v[194:197], v[124:127]
	v_mfma_f32_16x16x32_bf16 v[120:123], v[170:173], v[194:197], v[120:123]
	v_mfma_f32_16x16x32_bf16 v[108:111], v[162:165], v[202:205], v[108:111]
	v_mfma_f32_16x16x32_bf16 v[104:107], v[170:173], v[202:205], v[104:107]
	v_mfma_f32_16x16x32_bf16 v[92:95], v[162:165], v[214:217], v[92:95]
	v_mfma_f32_16x16x32_bf16 v[88:91], v[170:173], v[214:217], v[88:91]
	v_mfma_f32_16x16x32_bf16 v[76:79], v[162:165], v[222:225], v[76:79]
	v_mfma_f32_16x16x32_bf16 v[72:75], v[170:173], v[222:225], v[72:75]
	s_nop 0
	s_nop 0
	v_mfma_f32_16x16x32_bf16 v[116:119], v[174:177], v[190:193], v[116:119]
	v_mfma_f32_16x16x32_bf16 v[112:115], v[182:185], v[190:193], v[112:115]
	v_mfma_f32_16x16x32_bf16 v[100:103], v[174:177], v[198:201], v[100:103]
	v_mfma_f32_16x16x32_bf16 v[96:99], v[182:185], v[198:201], v[96:99]
	v_mfma_f32_16x16x32_bf16 v[84:87], v[174:177], v[210:213], v[84:87]
	v_mfma_f32_16x16x32_bf16 v[80:83], v[182:185], v[210:213], v[80:83]
	v_mfma_f32_16x16x32_bf16 v[68:71], v[174:177], v[218:221], v[68:71]
	v_mfma_f32_16x16x32_bf16 v[64:67], v[182:185], v[218:221], v[64:67]
	v_mfma_f32_16x16x32_bf16 v[116:119], v[178:181], v[194:197], v[116:119]
	v_mfma_f32_16x16x32_bf16 v[112:115], v[186:189], v[194:197], v[112:115]
	v_mfma_f32_16x16x32_bf16 v[100:103], v[178:181], v[202:205], v[100:103]
	v_mfma_f32_16x16x32_bf16 v[96:99], v[186:189], v[202:205], v[96:99]
	v_mfma_f32_16x16x32_bf16 v[84:87], v[178:181], v[214:217], v[84:87]
	v_mfma_f32_16x16x32_bf16 v[80:83], v[186:189], v[214:217], v[80:83]
	v_mfma_f32_16x16x32_bf16 v[68:71], v[178:181], v[222:225], v[68:71]
	v_mfma_f32_16x16x32_bf16 v[64:67], v[186:189], v[222:225], v[64:67]
	s_nop 0
	s_barrier
; #define PG8_STAGE(bufoff, gbase, voff) do { _Pragma("unroll") for (int _i = 0; _i < 2; ++_i) \
;         __builtin_amdgcn_global_load_lds((const unsigned*)((const char*)(gbase) + (voff)[_i]), (LAS unsigned*)(lds + (bufoff) + ldsw + _i * 8192), 16, 0, 0); } while (0)
; #define PG8_LDA(dst, b, h) do { _Pragma("unroll") for (int m = 0; m < 4; ++m) _Pragma("unroll") for (int k = 0; k < 2; ++k) dst[m][k] = *(const LAS bf16x8*)(lds + PG8_SA(b, h) + aoff + m * 2048 + k * 1024); } while (0)
; #define PG8_MMA(ai, bj, At, Bt) do { __builtin_amdgcn_s_setprio(1); _Pragma("unroll") for (int m = 0; m < 4; ++m) _Pragma("unroll") for (int n = 0; n < 2; ++n) _Pragma("unroll") for (int k = 0; k < 2; ++k) \
;         acc[ai][bj][m][n] = __builtin_amdgcn_mfma_f32_16x16x32_bf16(Bt[n][k], At[m][k], acc[ai][bj][m][n], 0, 0, 0); __builtin_amdgcn_s_setprio(0); } while (0)
; #define PG8_WAIT_V(n) asm volatile("s_waitcnt vmcnt(" #n ")" ::: "memory")
; #define PG8_WAIT_L(n) asm volatile("s_waitcnt lgkmcnt(" #n ")" ::: "memory")
; #define PG8_BAR __builtin_amdgcn_s_barrier()
; #define PG8_SCHED __builtin_amdgcn_sched_barrier(0)
; template <class Epi, class Sched>
; __device__ __forceinline__ void gemm_phase(LAS unsigned char* lds, const Gemm g, const Sched& S, const Epi& E, const int wave_s) {
;     ...
;             PG8_LDA(At, 1, 1); PG8_STAGE(PG8_SB(1, 0), b3, voffB); PG8_STAGE(PG8_SB(1, 1), b3 + hstepB, voffB); PG8_STAGE(PG8_SA(1, 0), a3, voffA);
;             PG8_WAIT_V(8); PG8_WAIT_L(0); PG8_BAR; PG8_MMA(1, 0, At, B0); PG8_MMA(1, 1, At, B1); PG8_BAR; PG8_SCHED;
;         }
	s_add_i32 s22, s49, s81
	v_lshl_add_u64 v[150:151], v[150:151], 0, s[14:15]
	s_mov_b32 m0, s22
	ds_read_b128 v[190:193], v157 offset:49152
	ds_read_b128 v[194:197], v157 offset:50176
	ds_read_b128 v[198:201], v157 offset:51200
	ds_read_b128 v[202:205], v157 offset:52224
	ds_read_b128 v[210:213], v157 offset:53248
	ds_read_b128 v[214:217], v157 offset:54272
	ds_read_b128 v[218:221], v157 offset:55296
	ds_read_b128 v[222:225], v157 offset:56320
	global_load_lds_dwordx4 v[150:151], off
	s_add_i32 m0, s22, 0x2000
	s_add_u32 s8, s8, 0x18080
	v_lshl_add_u64 v[150:151], v[206:207], 0, s[14:15]
	s_addc_u32 s9, s9, 0
	s_add_i32 s22, s50, s81
	global_load_lds_dwordx4 v[150:151], off
	v_lshl_add_u64 v[150:151], s[8:9], 0, v[130:131]
	s_mov_b32 m0, s22
	s_nop 0
	global_load_lds_dwordx4 v[150:151], off
	v_lshl_add_u64 v[150:151], s[8:9], 0, v[134:135]
	s_add_i32 m0, s22, 0x2000
	s_nop 0
	global_load_lds_dwordx4 v[150:151], off
	v_lshl_add_u64 v[150:151], v[226:227], 0, s[14:15]
	s_mov_b32 m0, s33
	s_nop 0
	global_load_lds_dwordx4 v[150:151], off
	v_lshl_add_u64 v[150:151], v[228:229], 0, s[14:15]
	s_mov_b32 m0, s34
	s_nop 0
	global_load_lds_dwordx4 v[150:151], off
	s_waitcnt vmcnt(8) lgkmcnt(0)
	s_barrier
	s_nop 0
	v_mfma_f32_16x16x32_bf16 v[60:63], v[158:161], v[190:193], v[60:63]
	v_mfma_f32_16x16x32_bf16 v[56:59], v[166:169], v[190:193], v[56:59]
	v_mfma_f32_16x16x32_bf16 v[44:47], v[158:161], v[198:201], v[44:47]
	v_mfma_f32_16x16x32_bf16 v[40:43], v[166:169], v[198:201], v[40:43]
	v_mfma_f32_16x16x32_bf16 v[28:31], v[158:161], v[210:213], v[28:31]
	v_mfma_f32_16x16x32_bf16 v[24:27], v[166:169], v[210:213], v[24:27]
	v_mfma_f32_16x16x32_bf16 v[12:15], v[158:161], v[218:221], v[12:15]
	v_mfma_f32_16x16x32_bf16 v[8:11], v[166:169], v[218:221], v[8:11]
	v_mfma_f32_16x16x32_bf16 v[60:63], v[162:165], v[194:197], v[60:63]
	v_mfma_f32_16x16x32_bf16 v[56:59], v[170:173], v[194:197], v[56:59]
	v_mfma_f32_16x16x32_bf16 v[44:47], v[162:165], v[202:205], v[44:47]
	v_mfma_f32_16x16x32_bf16 v[40:43], v[170:173], v[202:205], v[40:43]
	v_mfma_f32_16x16x32_bf16 v[28:31], v[162:165], v[214:217], v[28:31]
	v_mfma_f32_16x16x32_bf16 v[24:27], v[170:173], v[214:217], v[24:27]
	v_mfma_f32_16x16x32_bf16 v[12:15], v[162:165], v[222:225], v[12:15]
	v_mfma_f32_16x16x32_bf16 v[8:11], v[170:173], v[222:225], v[8:11]
	s_nop 0
	s_nop 0
	v_mfma_f32_16x16x32_bf16 v[52:55], v[174:177], v[190:193], v[52:55]
	v_mfma_f32_16x16x32_bf16 v[48:51], v[182:185], v[190:193], v[48:51]
	v_mfma_f32_16x16x32_bf16 v[36:39], v[174:177], v[198:201], v[36:39]
	v_mfma_f32_16x16x32_bf16 v[32:35], v[182:185], v[198:201], v[32:35]
	v_mfma_f32_16x16x32_bf16 v[20:23], v[174:177], v[210:213], v[20:23]
	v_mfma_f32_16x16x32_bf16 v[16:19], v[182:185], v[210:213], v[16:19]
	v_mfma_f32_16x16x32_bf16 v[4:7], v[174:177], v[218:221], v[4:7]
	v_mfma_f32_16x16x32_bf16 v[0:3], v[182:185], v[218:221], v[0:3]
	v_mfma_f32_16x16x32_bf16 v[52:55], v[178:181], v[194:197], v[52:55]
	v_mfma_f32_16x16x32_bf16 v[48:51], v[186:189], v[194:197], v[48:51]
	v_mfma_f32_16x16x32_bf16 v[36:39], v[178:181], v[202:205], v[36:39]
	v_mfma_f32_16x16x32_bf16 v[32:35], v[186:189], v[202:205], v[32:35]
	v_mfma_f32_16x16x32_bf16 v[20:23], v[178:181], v[214:217], v[20:23]
	v_mfma_f32_16x16x32_bf16 v[16:19], v[186:189], v[214:217], v[16:19]
	v_mfma_f32_16x16x32_bf16 v[4:7], v[178:181], v[222:225], v[4:7]
	v_mfma_f32_16x16x32_bf16 v[0:3], v[186:189], v[222:225], v[0:3]
	s_nop 0
	s_barrier
	s_add_i32 s48, s48, 2
	s_add_u32 s46, s46, 0x100
	s_addc_u32 s47, s47, 0
	s_cmp_gt_u32 s48, 3
	s_mov_b64 s[22:23], s[4:5]
	s_cbranch_scc0 .LBB0_375
	s_and_b64 vcc, exec, s[16:17]
	s_cbranch_vccz .LBB0_378
	s_barrier

; #define PG8_STAGE(bufoff, gbase, voff) do { _Pragma("unroll") for (int _i = 0; _i < 2; ++_i) \
;         __builtin_amdgcn_global_load_lds((const unsigned*)((const char*)(gbase) + (voff)[_i]), (LAS unsigned*)(lds + (bufoff) + ldsw + _i * 8192), 16, 0, 0); } while (0)
; #define PG8_LDA(dst, b, h) do { _Pragma("unroll") for (int m = 0; m < 4; ++m) _Pragma("unroll") for (int k = 0; k < 2; ++k) dst[m][k] = *(const LAS bf16x8*)(lds + PG8_SA(b, h) + aoff + m * 2048 + k * 1024); } while (0)
; #define PG8_LDB(dst, b, h) do { _Pragma("unroll") for (int n = 0; n < 2; ++n) _Pragma("unroll") for (int k = 0; k < 2; ++k) dst[n][k] = *(const LAS bf16x8*)(lds + PG8_SB(b, h) + boff + n * 2048 + k * 1024); } while (0)
; #define PG8_MMA(ai, bj, At, Bt) do { __builtin_amdgcn_s_setprio(1); _Pragma("unroll") for (int m = 0; m < 4; ++m) _Pragma("unroll") for (int n = 0; n < 2; ++n) _Pragma("unroll") for (int k = 0; k < 2; ++k) \
;         acc[ai][bj][m][n] = __builtin_amdgcn_mfma_f32_16x16x32_bf16(Bt[n][k], At[m][k], acc[ai][bj][m][n], 0, 0, 0); __builtin_amdgcn_s_setprio(0); } while (0)
; template <class Epi, class Sched>
; __device__ __forceinline__ void gemm_phase(LAS unsigned char* lds, const Gemm g, const Sched& S, const Epi& E, const int wave_s) {
;     ...
;         const bool has_next = S.next(ui + 1, nxt);
;         const char* nA = has_next ? (const char*)g.A + (size_t)nxt.pm * tstepA + (size_t)nxt.acol * 2 : cA; const char* nB = has_next ? (const char*)g.Bt + (size_t)nxt.pn * tstepB : cB;
; #pragma unroll 1
;         for (int t = 0; t < nt; t += 2) {
;             const bool last = (t == nt - 2);
;             const char* a1 = cA + (size_t)(t + 1) * kstep;
;             const char* a2 = last ? nA : cA + (size_t)(t + 2) * kstep; const char* b2 = last ? nB : cB + (size_t)(t + 2) * kstep;
;             const char* a3 = a2 + kstep; const char* b3 = b2 + kstep;
;             PG8_LDB(B0, 0, 0); PG8_LDB(B1, 0, 1); PG8_SCHED; PG8_LDA(At, 0, 0); PG8_STAGE(PG8_SA(1, 1), a1 + hstepA, voffA);
;             PG8_WAIT_V(8); PG8_WAIT_L(0); PG8_BAR; PG8_MMA(0, 0, At, B0); PG8_MMA(0, 1, At, B1); PG8_BAR; PG8_SCHED;
;             PG8_LDA(At, 0, 1); PG8_STAGE(PG8_SB(0, 0), b2, voffB); PG8_STAGE(PG8_SB(0, 1), b2 + hstepB, voffB); PG8_STAGE(PG8_SA(0, 0), a2, voffA);
;             PG8_WAIT_V(8); PG8_WAIT_L(0); PG8_BAR; PG8_MMA(1, 0, At, B0); PG8_MMA(1, 1, At, B1); PG8_BAR; PG8_SCHED;
.LBB0_417:
	s_add_u32 s39, s36, s38
	s_addc_u32 s44, s37, 0
	s_add_u32 s42, s39, 0x100
	s_addc_u32 s43, s44, 0
	s_and_b64 s[40:41], s[4:5], exec
	s_cselect_b32 s41, s29, s43
	s_cselect_b32 s40, s28, s42
	s_add_u32 s38, s34, s38
	s_addc_u32 s42, s35, 0
	s_add_u32 s38, s38, 0x100
	s_addc_u32 s42, s42, 0
	s_and_b64 s[4:5], s[4:5], exec
	s_cselect_b32 s43, s27, s42
	s_cselect_b32 s42, s68, s38
	s_add_u32 s46, s39, 0xf0080
	ds_read_b128 v[148:151], v145
	ds_read_b128 v[152:155], v145 offset:1024
	ds_read_b128 v[156:159], v145 offset:2048
	ds_read_b128 v[160:163], v145 offset:3072
	ds_read_b128 v[164:167], v146
	ds_read_b128 v[168:171], v146 offset:1024
	ds_read_b128 v[172:175], v146 offset:2048
	ds_read_b128 v[176:179], v146 offset:3072
	s_addc_u32 s47, s44, 0
	s_add_i32 s76, s59, s81
	s_add_i32 m0, s49, 0xc000
	s_add_i32 s79, s49, 0xe000
	s_add_i32 s73, s76, 0x2000
	s_add_u32 s44, s42, 0x10000
	s_addc_u32 s45, s43, 0
	s_add_i32 s75, s60, s81
	s_add_i32 s74, s75, 0x2000
	s_add_i32 s72, 0, 0x18000
	s_add_i32 s71, 0, 0x1c000
	s_add_u32 s38, s40, 0xf0000
	s_addc_u32 s39, s41, 0
	s_add_i32 s70, s72, s81
	s_add_i32 s69, s70, 0x2000
	s_add_u32 s4, s42, 0x10080
	s_addc_u32 s5, s43, 0
	s_add_i32 s78, s71, s81
	s_add_i32 s77, s78, 0x2000
	v_lshl_add_u64 v[140:141], s[46:47], 0, v[128:129]
	ds_read_b128 v[180:183], v147
	ds_read_b128 v[184:187], v147 offset:1024
	ds_read_b128 v[188:191], v147 offset:2048
	ds_read_b128 v[192:195], v147 offset:3072
	ds_read_b128 v[196:199], v147 offset:4096
	ds_read_b128 v[200:203], v147 offset:5120
	ds_read_b128 v[204:207], v147 offset:6144
	ds_read_b128 v[210:213], v147 offset:7168
	global_load_lds_dwordx4 v[140:141], off
	v_lshl_add_u64 v[140:141], s[46:47], 0, v[132:133]
	s_mov_b32 m0, s79
	s_nop 0
	global_load_lds_dwordx4 v[140:141], off
	s_waitcnt vmcnt(8) lgkmcnt(0)
	s_barrier
	s_nop 0
	v_mfma_f32_16x16x32_bf16 v[124:127], v[148:151], v[180:183], v[124:127]
	v_mfma_f32_16x16x32_bf16 v[120:123], v[156:159], v[180:183], v[120:123]
	v_mfma_f32_16x16x32_bf16 v[116:119], v[148:151], v[188:191], v[116:119]
	v_mfma_f32_16x16x32_bf16 v[108:111], v[156:159], v[188:191], v[108:111]
	v_mfma_f32_16x16x32_bf16 v[100:103], v[148:151], v[196:199], v[100:103]
	v_mfma_f32_16x16x32_bf16 v[92:95], v[156:159], v[196:199], v[92:95]
	v_mfma_f32_16x16x32_bf16 v[84:87], v[148:151], v[204:207], v[84:87]
	v_mfma_f32_16x16x32_bf16 v[76:79], v[156:159], v[204:207], v[76:79]
	v_mfma_f32_16x16x32_bf16 v[124:127], v[152:155], v[184:187], v[124:127]
	v_mfma_f32_16x16x32_bf16 v[120:123], v[160:163], v[184:187], v[120:123]
	v_mfma_f32_16x16x32_bf16 v[116:119], v[152:155], v[192:195], v[116:119]
	v_mfma_f32_16x16x32_bf16 v[108:111], v[160:163], v[192:195], v[108:111]
	v_mfma_f32_16x16x32_bf16 v[100:103], v[152:155], v[200:203], v[100:103]
	v_mfma_f32_16x16x32_bf16 v[92:95], v[160:163], v[200:203], v[92:95]
	v_mfma_f32_16x16x32_bf16 v[84:87], v[152:155], v[210:213], v[84:87]
	v_mfma_f32_16x16x32_bf16 v[76:79], v[160:163], v[210:213], v[76:79]
	s_nop 0
	s_nop 0
	v_mfma_f32_16x16x32_bf16 v[112:115], v[164:167], v[180:183], v[112:115]
	v_mfma_f32_16x16x32_bf16 v[104:107], v[172:175], v[180:183], v[104:107]
	v_mfma_f32_16x16x32_bf16 v[96:99], v[164:167], v[188:191], v[96:99]
	v_mfma_f32_16x16x32_bf16 v[88:91], v[172:175], v[188:191], v[88:91]
	v_mfma_f32_16x16x32_bf16 v[80:83], v[164:167], v[196:199], v[80:83]
	v_mfma_f32_16x16x32_bf16 v[72:75], v[172:175], v[196:199], v[72:75]
	v_mfma_f32_16x16x32_bf16 v[68:71], v[164:167], v[204:207], v[68:71]
	v_mfma_f32_16x16x32_bf16 v[64:67], v[172:175], v[204:207], v[64:67]
	v_mfma_f32_16x16x32_bf16 v[112:115], v[168:171], v[184:187], v[112:115]
	v_mfma_f32_16x16x32_bf16 v[104:107], v[176:179], v[184:187], v[104:107]
	v_mfma_f32_16x16x32_bf16 v[96:99], v[168:171], v[192:195], v[96:99]
	v_mfma_f32_16x16x32_bf16 v[88:91], v[176:179], v[192:195], v[88:91]
	v_mfma_f32_16x16x32_bf16 v[80:83], v[168:171], v[200:203], v[80:83]
	v_mfma_f32_16x16x32_bf16 v[72:75], v[176:179], v[200:203], v[72:75]
	v_mfma_f32_16x16x32_bf16 v[68:71], v[168:171], v[210:213], v[68:71]
	v_mfma_f32_16x16x32_bf16 v[64:67], v[176:179], v[210:213], v[64:67]
	s_nop 0
	s_barrier
	s_mov_b32 m0, s76
	v_lshl_add_u64 v[140:141], s[42:43], 0, v[130:131]
	ds_read_b128 v[180:183], v147 offset:16384
	ds_read_b128 v[184:187], v147 offset:17408
	ds_read_b128 v[188:191], v147 offset:18432
	ds_read_b128 v[192:195], v147 offset:19456
	ds_read_b128 v[196:199], v147 offset:20480
	ds_read_b128 v[200:203], v147 offset:21504
	ds_read_b128 v[204:207], v147 offset:22528
	ds_read_b128 v[210:213], v147 offset:23552
	global_load_lds_dwordx4 v[140:141], off
	v_lshl_add_u64 v[214:215], s[42:43], 0, v[134:135]
	s_mov_b32 m0, s73
	v_lshl_add_u64 v[216:217], s[44:45], 0, v[130:131]
	global_load_lds_dwordx4 v[214:215], off
	s_mov_b32 m0, s75
	v_lshl_add_u64 v[218:219], s[40:41], 0, v[132:133]
	global_load_lds_dwordx4 v[216:217], off
	v_lshl_add_u64 v[216:217], s[44:45], 0, v[134:135]
	s_mov_b32 m0, s74
	s_nop 0
	global_load_lds_dwordx4 v[216:217], off
	v_lshl_add_u64 v[216:217], s[40:41], 0, v[128:129]
	s_mov_b32 m0, s49
	s_nop 0
	global_load_lds_dwordx4 v[216:217], off
	s_mov_b32 m0, s50
	s_nop 0
	global_load_lds_dwordx4 v[218:219], off
	s_waitcnt vmcnt(8) lgkmcnt(0)
	s_barrier
; #define PG8_STAGE(bufoff, gbase, voff) do { _Pragma("unroll") for (int _i = 0; _i < 2; ++_i) \
;         __builtin_amdgcn_global_load_lds((const unsigned*)((const char*)(gbase) + (voff)[_i]), (LAS unsigned*)(lds + (bufoff) + ldsw + _i * 8192), 16, 0, 0); } while (0)
; #define PG8_LDA(dst, b, h) do { _Pragma("unroll") for (int m = 0; m < 4; ++m) _Pragma("unroll") for (int k = 0; k < 2; ++k) dst[m][k] = *(const LAS bf16x8*)(lds + PG8_SA(b, h) + aoff + m * 2048 + k * 1024); } while (0)
; #define PG8_LDB(dst, b, h) do { _Pragma("unroll") for (int n = 0; n < 2; ++n) _Pragma("unroll") for (int k = 0; k < 2; ++k) dst[n][k] = *(const LAS bf16x8*)(lds + PG8_SB(b, h) + boff + n * 2048 + k * 1024); } while (0)
; #define PG8_MMA(ai, bj, At, Bt) do { __builtin_amdgcn_s_setprio(1); _Pragma("unroll") for (int m = 0; m < 4; ++m) _Pragma("unroll") for (int n = 0; n < 2; ++n) _Pragma("unroll") for (int k = 0; k < 2; ++k) \
;         acc[ai][bj][m][n] = __builtin_amdgcn_mfma_f32_16x16x32_bf16(Bt[n][k], At[m][k], acc[ai][bj][m][n], 0, 0, 0); __builtin_amdgcn_s_setprio(0); } while (0)
; #define PG8_WAIT_V(n) asm volatile("s_waitcnt vmcnt(" #n ")" ::: "memory")
; #define PG8_WAIT_L(n) asm volatile("s_waitcnt lgkmcnt(" #n ")" ::: "memory")
; #define PG8_BAR __builtin_amdgcn_s_barrier()
; #define PG8_SCHED __builtin_amdgcn_sched_barrier(0)
; template <class Epi, class Sched>
; __device__ __forceinline__ void gemm_phase(LAS unsigned char* lds, const Gemm g, const Sched& S, const Epi& E, const int wave_s) {
;     ...
;             PG8_WAIT_V(8); PG8_WAIT_L(0); PG8_BAR; PG8_MMA(1, 0, At, B0); PG8_MMA(1, 1, At, B1); PG8_BAR; PG8_SCHED;
;             PG8_LDB(B0, 1, 0); PG8_LDB(B1, 1, 1); PG8_SCHED; PG8_LDA(At, 1, 0); PG8_STAGE(PG8_SA(0, 1), a2 + hstepA, voffA);
;             PG8_WAIT_V(8); PG8_WAIT_L(0); PG8_BAR; PG8_MMA(0, 0, At, B0); PG8_MMA(0, 1, At, B1); PG8_BAR; PG8_SCHED;
	s_nop 0
	v_mfma_f32_16x16x32_bf16 v[60:63], v[148:151], v[180:183], v[60:63]
	v_mfma_f32_16x16x32_bf16 v[56:59], v[156:159], v[180:183], v[56:59]
	v_mfma_f32_16x16x32_bf16 v[52:55], v[148:151], v[188:191], v[52:55]
	v_mfma_f32_16x16x32_bf16 v[44:47], v[156:159], v[188:191], v[44:47]
	v_mfma_f32_16x16x32_bf16 v[36:39], v[148:151], v[196:199], v[36:39]
	v_mfma_f32_16x16x32_bf16 v[28:31], v[156:159], v[196:199], v[28:31]
	v_mfma_f32_16x16x32_bf16 v[20:23], v[148:151], v[204:207], v[20:23]
	v_mfma_f32_16x16x32_bf16 v[12:15], v[156:159], v[204:207], v[12:15]
	v_mfma_f32_16x16x32_bf16 v[60:63], v[152:155], v[184:187], v[60:63]
	v_mfma_f32_16x16x32_bf16 v[56:59], v[160:163], v[184:187], v[56:59]
	v_mfma_f32_16x16x32_bf16 v[52:55], v[152:155], v[192:195], v[52:55]
	v_mfma_f32_16x16x32_bf16 v[44:47], v[160:163], v[192:195], v[44:47]
	v_mfma_f32_16x16x32_bf16 v[36:39], v[152:155], v[200:203], v[36:39]
	v_mfma_f32_16x16x32_bf16 v[28:31], v[160:163], v[200:203], v[28:31]
	v_mfma_f32_16x16x32_bf16 v[20:23], v[152:155], v[210:213], v[20:23]
	v_mfma_f32_16x16x32_bf16 v[12:15], v[160:163], v[210:213], v[12:15]
	s_nop 0
	s_nop 0
	v_mfma_f32_16x16x32_bf16 v[48:51], v[164:167], v[180:183], v[48:51]
	v_mfma_f32_16x16x32_bf16 v[40:43], v[172:175], v[180:183], v[40:43]
	v_mfma_f32_16x16x32_bf16 v[32:35], v[164:167], v[188:191], v[32:35]
	v_mfma_f32_16x16x32_bf16 v[24:27], v[172:175], v[188:191], v[24:27]
	v_mfma_f32_16x16x32_bf16 v[16:19], v[164:167], v[196:199], v[16:19]
	v_mfma_f32_16x16x32_bf16 v[8:11], v[172:175], v[196:199], v[8:11]
	v_mfma_f32_16x16x32_bf16 v[4:7], v[164:167], v[204:207], v[4:7]
	v_mfma_f32_16x16x32_bf16 v[0:3], v[172:175], v[204:207], v[0:3]
	v_mfma_f32_16x16x32_bf16 v[48:51], v[168:171], v[184:187], v[48:51]
	v_mfma_f32_16x16x32_bf16 v[40:43], v[176:179], v[184:187], v[40:43]
	v_mfma_f32_16x16x32_bf16 v[32:35], v[168:171], v[192:195], v[32:35]
	v_mfma_f32_16x16x32_bf16 v[24:27], v[176:179], v[192:195], v[24:27]
	v_mfma_f32_16x16x32_bf16 v[16:19], v[168:171], v[200:203], v[16:19]
	v_mfma_f32_16x16x32_bf16 v[8:11], v[176:179], v[200:203], v[8:11]
	v_mfma_f32_16x16x32_bf16 v[4:7], v[168:171], v[210:213], v[4:7]
	v_mfma_f32_16x16x32_bf16 v[0:3], v[176:179], v[210:213], v[0:3]
	s_nop 0
	s_barrier
	v_add_u32_e32 v160, s72, v143
	v_add_u32_e32 v176, s71, v143
	ds_read_b128 v[148:151], v160
	ds_read_b128 v[152:155], v160 offset:1024
	ds_read_b128 v[156:159], v160 offset:2048
	ds_read_b128 v[160:163], v160 offset:3072
	ds_read_b128 v[164:167], v176
	ds_read_b128 v[168:171], v176 offset:1024
	ds_read_b128 v[172:175], v176 offset:2048
	ds_read_b128 v[176:179], v176 offset:3072
	s_mov_b32 m0, s51
	v_lshl_add_u64 v[220:221], s[38:39], 0, v[128:129]
	ds_read_b128 v[180:183], v147 offset:32768
	ds_read_b128 v[184:187], v147 offset:33792
	ds_read_b128 v[188:191], v147 offset:34816
	ds_read_b128 v[192:195], v147 offset:35840
	ds_read_b128 v[196:199], v147 offset:36864
	ds_read_b128 v[200:203], v147 offset:37888
	ds_read_b128 v[204:207], v147 offset:38912
	ds_read_b128 v[210:213], v147 offset:39936
	global_load_lds_dwordx4 v[220:221], off
	v_lshl_add_u64 v[220:221], s[38:39], 0, v[132:133]
	s_mov_b32 m0, s52
	s_nop 0
	global_load_lds_dwordx4 v[220:221], off
	s_waitcnt vmcnt(8) lgkmcnt(0)
	s_barrier
	s_nop 0
	v_mfma_f32_16x16x32_bf16 v[124:127], v[148:151], v[180:183], v[124:127]
	v_mfma_f32_16x16x32_bf16 v[120:123], v[156:159], v[180:183], v[120:123]
	v_mfma_f32_16x16x32_bf16 v[116:119], v[148:151], v[188:191], v[116:119]
	v_mfma_f32_16x16x32_bf16 v[108:111], v[156:159], v[188:191], v[108:111]
	v_mfma_f32_16x16x32_bf16 v[100:103], v[148:151], v[196:199], v[100:103]
	v_mfma_f32_16x16x32_bf16 v[92:95], v[156:159], v[196:199], v[92:95]
	v_mfma_f32_16x16x32_bf16 v[84:87], v[148:151], v[204:207], v[84:87]
	v_mfma_f32_16x16x32_bf16 v[76:79], v[156:159], v[204:207], v[76:79]
	v_mfma_f32_16x16x32_bf16 v[124:127], v[152:155], v[184:187], v[124:127]
	v_mfma_f32_16x16x32_bf16 v[120:123], v[160:163], v[184:187], v[120:123]
	v_mfma_f32_16x16x32_bf16 v[116:119], v[152:155], v[192:195], v[116:119]
	v_mfma_f32_16x16x32_bf16 v[108:111], v[160:163], v[192:195], v[108:111]
	v_mfma_f32_16x16x32_bf16 v[100:103], v[152:155], v[200:203], v[100:103]
	v_mfma_f32_16x16x32_bf16 v[92:95], v[160:163], v[200:203], v[92:95]
	v_mfma_f32_16x16x32_bf16 v[84:87], v[152:155], v[210:213], v[84:87]
	v_mfma_f32_16x16x32_bf16 v[76:79], v[160:163], v[210:213], v[76:79]
	s_nop 0
	s_nop 0
	v_mfma_f32_16x16x32_bf16 v[112:115], v[164:167], v[180:183], v[112:115]
	v_mfma_f32_16x16x32_bf16 v[104:107], v[172:175], v[180:183], v[104:107]
	v_mfma_f32_16x16x32_bf16 v[96:99], v[164:167], v[188:191], v[96:99]
	v_mfma_f32_16x16x32_bf16 v[88:91], v[172:175], v[188:191], v[88:91]
	v_mfma_f32_16x16x32_bf16 v[80:83], v[164:167], v[196:199], v[80:83]
	v_mfma_f32_16x16x32_bf16 v[72:75], v[172:175], v[196:199], v[72:75]
	v_mfma_f32_16x16x32_bf16 v[68:71], v[164:167], v[204:207], v[68:71]
	v_mfma_f32_16x16x32_bf16 v[64:67], v[172:175], v[204:207], v[64:67]
	v_mfma_f32_16x16x32_bf16 v[112:115], v[168:171], v[184:187], v[112:115]
	v_mfma_f32_16x16x32_bf16 v[104:107], v[176:179], v[184:187], v[104:107]
	v_mfma_f32_16x16x32_bf16 v[96:99], v[168:171], v[192:195], v[96:99]
	v_mfma_f32_16x16x32_bf16 v[88:91], v[176:179], v[192:195], v[88:91]
	v_mfma_f32_16x16x32_bf16 v[80:83], v[168:171], v[200:203], v[80:83]
	v_mfma_f32_16x16x32_bf16 v[72:75], v[176:179], v[200:203], v[72:75]
	v_mfma_f32_16x16x32_bf16 v[68:71], v[168:171], v[210:213], v[68:71]
	v_mfma_f32_16x16x32_bf16 v[64:67], v[176:179], v[210:213], v[64:67]
	s_nop 0
	s_barrier
; #define PG8_STAGE(bufoff, gbase, voff) do { _Pragma("unroll") for (int _i = 0; _i < 2; ++_i) \
;         __builtin_amdgcn_global_load_lds((const unsigned*)((const char*)(gbase) + (voff)[_i]), (LAS unsigned*)(lds + (bufoff) + ldsw + _i * 8192), 16, 0, 0); } while (0)
; #define PG8_LDA(dst, b, h) do { _Pragma("unroll") for (int m = 0; m < 4; ++m) _Pragma("unroll") for (int k = 0; k < 2; ++k) dst[m][k] = *(const LAS bf16x8*)(lds + PG8_SA(b, h) + aoff + m * 2048 + k * 1024); } while (0)
; #define PG8_MMA(ai, bj, At, Bt) do { __builtin_amdgcn_s_setprio(1); _Pragma("unroll") for (int m = 0; m < 4; ++m) _Pragma("unroll") for (int n = 0; n < 2; ++n) _Pragma("unroll") for (int k = 0; k < 2; ++k) \
;         acc[ai][bj][m][n] = __builtin_amdgcn_mfma_f32_16x16x32_bf16(Bt[n][k], At[m][k], acc[ai][bj][m][n], 0, 0, 0); __builtin_amdgcn_s_setprio(0); } while (0)
; #define PG8_WAIT_V(n) asm volatile("s_waitcnt vmcnt(" #n ")" ::: "memory")
; #define PG8_WAIT_L(n) asm volatile("s_waitcnt lgkmcnt(" #n ")" ::: "memory")
; #define PG8_BAR __builtin_amdgcn_s_barrier()
; #define PG8_SCHED __builtin_amdgcn_sched_barrier(0)
; template <class Epi, class Sched>
; __device__ __forceinline__ void gemm_phase(LAS unsigned char* lds, const Gemm g, const Sched& S, const Epi& E, const int wave_s) {
;     ...
;             PG8_LDA(At, 1, 1); PG8_STAGE(PG8_SB(1, 0), b3, voffB); PG8_STAGE(PG8_SB(1, 1), b3 + hstepB, voffB); PG8_STAGE(PG8_SA(1, 0), a3, voffA);
;             PG8_WAIT_V(8); PG8_WAIT_L(0); PG8_BAR; PG8_MMA(1, 0, At, B0); PG8_MMA(1, 1, At, B1); PG8_BAR; PG8_SCHED;
;         }
	s_mov_b32 m0, s70
	v_lshl_add_u64 v[140:141], v[140:141], 0, s[14:15]
	ds_read_b128 v[180:183], v147 offset:49152
	ds_read_b128 v[184:187], v147 offset:50176
	ds_read_b128 v[188:191], v147 offset:51200
	ds_read_b128 v[192:195], v147 offset:52224
	ds_read_b128 v[196:199], v147 offset:53248
	ds_read_b128 v[200:203], v147 offset:54272
	ds_read_b128 v[204:207], v147 offset:55296
	ds_read_b128 v[210:213], v147 offset:56320
	global_load_lds_dwordx4 v[140:141], off
	v_lshl_add_u64 v[140:141], v[214:215], 0, s[14:15]
	s_mov_b32 m0, s69
	s_nop 0
	global_load_lds_dwordx4 v[140:141], off
	v_lshl_add_u64 v[140:141], s[4:5], 0, v[130:131]
	s_mov_b32 m0, s78
	s_nop 0
	global_load_lds_dwordx4 v[140:141], off
	v_lshl_add_u64 v[140:141], s[4:5], 0, v[134:135]
	s_mov_b32 m0, s77
	s_nop 0
	global_load_lds_dwordx4 v[140:141], off
	v_lshl_add_u64 v[140:141], v[216:217], 0, s[14:15]
	s_mov_b32 m0, s54
	s_nop 0
	global_load_lds_dwordx4 v[140:141], off
	v_lshl_add_u64 v[140:141], v[218:219], 0, s[14:15]
	s_mov_b32 m0, s55
	s_nop 0
	global_load_lds_dwordx4 v[140:141], off
	s_waitcnt vmcnt(8) lgkmcnt(0)
	s_barrier
	s_nop 0
	v_mfma_f32_16x16x32_bf16 v[60:63], v[148:151], v[180:183], v[60:63]
	v_mfma_f32_16x16x32_bf16 v[56:59], v[156:159], v[180:183], v[56:59]
	v_mfma_f32_16x16x32_bf16 v[52:55], v[148:151], v[188:191], v[52:55]
	v_mfma_f32_16x16x32_bf16 v[44:47], v[156:159], v[188:191], v[44:47]
	v_mfma_f32_16x16x32_bf16 v[36:39], v[148:151], v[196:199], v[36:39]
	v_mfma_f32_16x16x32_bf16 v[28:31], v[156:159], v[196:199], v[28:31]
	v_mfma_f32_16x16x32_bf16 v[20:23], v[148:151], v[204:207], v[20:23]
	v_mfma_f32_16x16x32_bf16 v[12:15], v[156:159], v[204:207], v[12:15]
	v_mfma_f32_16x16x32_bf16 v[60:63], v[152:155], v[184:187], v[60:63]
	v_mfma_f32_16x16x32_bf16 v[56:59], v[160:163], v[184:187], v[56:59]
	v_mfma_f32_16x16x32_bf16 v[52:55], v[152:155], v[192:195], v[52:55]
	v_mfma_f32_16x16x32_bf16 v[44:47], v[160:163], v[192:195], v[44:47]
	v_mfma_f32_16x16x32_bf16 v[36:39], v[152:155], v[200:203], v[36:39]
	v_mfma_f32_16x16x32_bf16 v[28:31], v[160:163], v[200:203], v[28:31]
	v_mfma_f32_16x16x32_bf16 v[20:23], v[152:155], v[210:213], v[20:23]
	v_mfma_f32_16x16x32_bf16 v[12:15], v[160:163], v[210:213], v[12:15]
	s_nop 0
	s_nop 0
	v_mfma_f32_16x16x32_bf16 v[48:51], v[164:167], v[180:183], v[48:51]
	v_mfma_f32_16x16x32_bf16 v[40:43], v[172:175], v[180:183], v[40:43]
	v_mfma_f32_16x16x32_bf16 v[32:35], v[164:167], v[188:191], v[32:35]
	v_mfma_f32_16x16x32_bf16 v[24:27], v[172:175], v[188:191], v[24:27]
	v_mfma_f32_16x16x32_bf16 v[16:19], v[164:167], v[196:199], v[16:19]
	v_mfma_f32_16x16x32_bf16 v[8:11], v[172:175], v[196:199], v[8:11]
	v_mfma_f32_16x16x32_bf16 v[4:7], v[164:167], v[204:207], v[4:7]
	v_mfma_f32_16x16x32_bf16 v[0:3], v[172:175], v[204:207], v[0:3]
	v_mfma_f32_16x16x32_bf16 v[48:51], v[168:171], v[184:187], v[48:51]
	v_mfma_f32_16x16x32_bf16 v[40:43], v[176:179], v[184:187], v[40:43]
	v_mfma_f32_16x16x32_bf16 v[32:35], v[168:171], v[192:195], v[32:35]
	v_mfma_f32_16x16x32_bf16 v[24:27], v[176:179], v[192:195], v[24:27]
	v_mfma_f32_16x16x32_bf16 v[16:19], v[168:171], v[200:203], v[16:19]
	v_mfma_f32_16x16x32_bf16 v[8:11], v[176:179], v[200:203], v[8:11]
	v_mfma_f32_16x16x32_bf16 v[4:7], v[168:171], v[210:213], v[4:7]
	v_mfma_f32_16x16x32_bf16 v[0:3], v[176:179], v[210:213], v[0:3]
	s_nop 0
	s_barrier
	s_movk_i32 s38, 0x100
	s_andn2_b64 vcc, exec, s[8:9]
	s_mov_b64 s[4:5], -1
	s_mov_b64 s[8:9], 0
	s_cbranch_vccz .LBB0_417
	s_and_b64 vcc, exec, s[16:17]
	s_cbranch_vccz .LBB0_420
	s_barrier

; #define PG8_STAGE(bufoff, gbase, voff) do { _Pragma("unroll") for (int _i = 0; _i < 2; ++_i) \
;         __builtin_amdgcn_global_load_lds((const unsigned*)((const char*)(gbase) + (voff)[_i]), (LAS unsigned*)(lds + (bufoff) + ldsw + _i * 8192), 16, 0, 0); } while (0)
; #define PG8_LDA(dst, b, h) do { _Pragma("unroll") for (int m = 0; m < 4; ++m) _Pragma("unroll") for (int k = 0; k < 2; ++k) dst[m][k] = *(const LAS bf16x8*)(lds + PG8_SA(b, h) + aoff + m * 2048 + k * 1024); } while (0)
; #define PG8_LDB(dst, b, h) do { _Pragma("unroll") for (int n = 0; n < 2; ++n) _Pragma("unroll") for (int k = 0; k < 2; ++k) dst[n][k] = *(const LAS bf16x8*)(lds + PG8_SB(b, h) + boff + n * 2048 + k * 1024); } while (0)
; #define PG8_MMA(ai, bj, At, Bt) do { __builtin_amdgcn_s_setprio(1); _Pragma("unroll") for (int m = 0; m < 4; ++m) _Pragma("unroll") for (int n = 0; n < 2; ++n) _Pragma("unroll") for (int k = 0; k < 2; ++k) \
;         acc[ai][bj][m][n] = __builtin_amdgcn_mfma_f32_16x16x32_bf16(Bt[n][k], At[m][k], acc[ai][bj][m][n], 0, 0, 0); __builtin_amdgcn_s_setprio(0); } while (0)
; #define PG8_WAIT_V(n) asm volatile("s_waitcnt vmcnt(" #n ")" ::: "memory")
; #define PG8_WAIT_L(n) asm volatile("s_waitcnt lgkmcnt(" #n ")" ::: "memory")
; #define PG8_BAR __builtin_amdgcn_s_barrier()
; #define PG8_SCHED __builtin_amdgcn_sched_barrier(0)
; template <class Epi, class Sched>
; __device__ __forceinline__ void gemm_phase(LAS unsigned char* lds, const Gemm g, const Sched& S, const Epi& E, const int wave_s) {
;     ...
;             const bool last = (t == nt - 2);
;             const char* a1 = cA + (size_t)(t + 1) * kstep;
;             const char* a2 = last ? nA : cA + (size_t)(t + 2) * kstep; const char* b2 = last ? nB : cB + (size_t)(t + 2) * kstep;
;             const char* a3 = a2 + kstep; const char* b3 = b2 + kstep;
;             PG8_LDB(B0, 0, 0); PG8_LDB(B1, 0, 1); PG8_SCHED; PG8_LDA(At, 0, 0); PG8_STAGE(PG8_SA(1, 1), a1 + hstepA, voffA);
;             PG8_WAIT_V(8); PG8_WAIT_L(0); PG8_BAR; PG8_MMA(0, 0, At, B0); PG8_MMA(0, 1, At, B1); PG8_BAR; PG8_SCHED;
;             PG8_LDA(At, 0, 1); PG8_STAGE(PG8_SB(0, 0), b2, voffB); PG8_STAGE(PG8_SB(0, 1), b2 + hstepB, voffB); PG8_STAGE(PG8_SA(0, 0), a2, voffA);
;             PG8_WAIT_V(8); PG8_WAIT_L(0); PG8_BAR; PG8_MMA(1, 0, At, B0); PG8_MMA(1, 1, At, B1); PG8_BAR; PG8_SCHED;
.LBB0_860:
	ds_read_b128 v[100:103], v212
	ds_read_b128 v[108:111], v212 offset:1024
	ds_read_b128 v[136:139], v212 offset:2048
	ds_read_b128 v[140:143], v212 offset:3072
	ds_read_b128 v[144:147], v213
	ds_read_b128 v[148:151], v213 offset:1024
	ds_read_b128 v[152:155], v213 offset:2048
	ds_read_b128 v[156:159], v213 offset:3072
	s_add_u32 s4, s40, 0xfffc0080
	s_addc_u32 s5, s41, -1
	s_cmp_eq_u32 s54, 12
	s_cselect_b32 s43, s9, s5
	s_cselect_b32 s42, s27, s4
	s_cselect_b32 s5, s29, s53
	s_cselect_b32 s4, s31, s39
	v_lshl_add_u64 v[206:207], s[40:41], 0, v[178:179]
	s_add_i32 m0, s3, 0xc000
	ds_read_b128 v[160:163], v214
	ds_read_b128 v[164:167], v214 offset:1024
	ds_read_b128 v[186:189], v214 offset:2048
	ds_read_b128 v[190:193], v214 offset:3072
	ds_read_b128 v[194:197], v214 offset:4096
	ds_read_b128 v[198:201], v214 offset:5120
	ds_read_b128 v[202:205], v214 offset:6144
	ds_read_b128 v[216:219], v214 offset:7168
	global_load_lds_dwordx4 v[206:207], off
	v_lshl_add_u64 v[206:207], s[40:41], 0, v[180:181]
	s_add_i32 m0, s3, 0xe000
	s_nop 0
	global_load_lds_dwordx4 v[206:207], off
	s_waitcnt vmcnt(8) lgkmcnt(0)
	s_barrier
	s_nop 0
	v_mfma_f32_16x16x32_bf16 v[132:135], v[100:103], v[160:163], v[132:135]
	v_mfma_f32_16x16x32_bf16 v[128:131], v[136:139], v[160:163], v[128:131]
	v_mfma_f32_16x16x32_bf16 v[124:127], v[100:103], v[186:189], v[124:127]
	v_mfma_f32_16x16x32_bf16 v[120:123], v[136:139], v[186:189], v[120:123]
	v_mfma_f32_16x16x32_bf16 v[116:119], v[100:103], v[194:197], v[116:119]
	v_mfma_f32_16x16x32_bf16 v[112:115], v[136:139], v[194:197], v[112:115]
	v_mfma_f32_16x16x32_bf16 v[104:107], v[100:103], v[202:205], v[104:107]
	v_mfma_f32_16x16x32_bf16 v[96:99], v[136:139], v[202:205], v[96:99]
	v_mfma_f32_16x16x32_bf16 v[132:135], v[108:111], v[164:167], v[132:135]
	v_mfma_f32_16x16x32_bf16 v[128:131], v[140:143], v[164:167], v[128:131]
	v_mfma_f32_16x16x32_bf16 v[124:127], v[108:111], v[190:193], v[124:127]
	v_mfma_f32_16x16x32_bf16 v[120:123], v[140:143], v[190:193], v[120:123]
	v_mfma_f32_16x16x32_bf16 v[116:119], v[108:111], v[198:201], v[116:119]
	v_mfma_f32_16x16x32_bf16 v[112:115], v[140:143], v[198:201], v[112:115]
	v_mfma_f32_16x16x32_bf16 v[104:107], v[108:111], v[216:219], v[104:107]
	v_mfma_f32_16x16x32_bf16 v[96:99], v[140:143], v[216:219], v[96:99]
	s_nop 0
	s_nop 0
	v_mfma_f32_16x16x32_bf16 v[60:63], v[144:147], v[160:163], v[60:63]
	v_mfma_f32_16x16x32_bf16 v[56:59], v[152:155], v[160:163], v[56:59]
	v_mfma_f32_16x16x32_bf16 v[52:55], v[144:147], v[186:189], v[52:55]
	v_mfma_f32_16x16x32_bf16 v[48:51], v[152:155], v[186:189], v[48:51]
	v_mfma_f32_16x16x32_bf16 v[44:47], v[144:147], v[194:197], v[44:47]
	v_mfma_f32_16x16x32_bf16 v[40:43], v[152:155], v[194:197], v[40:43]
	v_mfma_f32_16x16x32_bf16 v[36:39], v[144:147], v[202:205], v[36:39]
	v_mfma_f32_16x16x32_bf16 v[32:35], v[152:155], v[202:205], v[32:35]
	v_mfma_f32_16x16x32_bf16 v[60:63], v[148:151], v[164:167], v[60:63]
	v_mfma_f32_16x16x32_bf16 v[56:59], v[156:159], v[164:167], v[56:59]
	v_mfma_f32_16x16x32_bf16 v[52:55], v[148:151], v[190:193], v[52:55]
	v_mfma_f32_16x16x32_bf16 v[48:51], v[156:159], v[190:193], v[48:51]
	v_mfma_f32_16x16x32_bf16 v[44:47], v[148:151], v[198:201], v[44:47]
	v_mfma_f32_16x16x32_bf16 v[40:43], v[156:159], v[198:201], v[40:43]
	v_mfma_f32_16x16x32_bf16 v[36:39], v[148:151], v[216:219], v[36:39]
	v_mfma_f32_16x16x32_bf16 v[32:35], v[156:159], v[216:219], v[32:35]
	s_nop 0
	s_barrier
	s_add_i32 s55, s50, s81
	v_lshl_add_u64 v[206:207], s[4:5], 0, v[170:171]
	s_mov_b32 m0, s55
	ds_read_b128 v[160:163], v214 offset:16384
	ds_read_b128 v[164:167], v214 offset:17408
	ds_read_b128 v[186:189], v214 offset:18432
	ds_read_b128 v[190:193], v214 offset:19456
	ds_read_b128 v[194:197], v214 offset:20480
	ds_read_b128 v[198:201], v214 offset:21504
	ds_read_b128 v[202:205], v214 offset:22528
	ds_read_b128 v[216:219], v214 offset:23552
	global_load_lds_dwordx4 v[206:207], off
	s_add_i32 m0, s55, 0x2000
	s_add_u32 s56, s4, 0x40000
	v_lshl_add_u64 v[220:221], s[4:5], 0, v[174:175]
	s_addc_u32 s57, s5, 0
	s_add_i32 s55, s51, s81
	global_load_lds_dwordx4 v[220:221], off
	v_lshl_add_u64 v[222:223], s[56:57], 0, v[170:171]
	s_mov_b32 m0, s55
	v_lshl_add_u64 v[224:225], s[42:43], 0, v[172:173]
	global_load_lds_dwordx4 v[222:223], off
	v_lshl_add_u64 v[222:223], s[56:57], 0, v[174:175]
	s_add_i32 m0, s55, 0x2000
	s_nop 0
	global_load_lds_dwordx4 v[222:223], off
	v_lshl_add_u64 v[222:223], s[42:43], 0, v[168:169]
	s_mov_b32 m0, s3
	s_nop 0
	global_load_lds_dwordx4 v[222:223], off
	s_mov_b32 m0, s33
	s_nop 0
	global_load_lds_dwordx4 v[224:225], off
	s_waitcnt vmcnt(8) lgkmcnt(0)
	s_barrier
; #define PG8_STAGE(bufoff, gbase, voff) do { _Pragma("unroll") for (int _i = 0; _i < 2; ++_i) \
;         __builtin_amdgcn_global_load_lds((const unsigned*)((const char*)(gbase) + (voff)[_i]), (LAS unsigned*)(lds + (bufoff) + ldsw + _i * 8192), 16, 0, 0); } while (0)
; #define PG8_LDA(dst, b, h) do { _Pragma("unroll") for (int m = 0; m < 4; ++m) _Pragma("unroll") for (int k = 0; k < 2; ++k) dst[m][k] = *(const LAS bf16x8*)(lds + PG8_SA(b, h) + aoff + m * 2048 + k * 1024); } while (0)
; #define PG8_LDB(dst, b, h) do { _Pragma("unroll") for (int n = 0; n < 2; ++n) _Pragma("unroll") for (int k = 0; k < 2; ++k) dst[n][k] = *(const LAS bf16x8*)(lds + PG8_SB(b, h) + boff + n * 2048 + k * 1024); } while (0)
; #define PG8_MMA(ai, bj, At, Bt) do { __builtin_amdgcn_s_setprio(1); _Pragma("unroll") for (int m = 0; m < 4; ++m) _Pragma("unroll") for (int n = 0; n < 2; ++n) _Pragma("unroll") for (int k = 0; k < 2; ++k) \
;         acc[ai][bj][m][n] = __builtin_amdgcn_mfma_f32_16x16x32_bf16(Bt[n][k], At[m][k], acc[ai][bj][m][n], 0, 0, 0); __builtin_amdgcn_s_setprio(0); } while (0)
; #define PG8_WAIT_V(n) asm volatile("s_waitcnt vmcnt(" #n ")" ::: "memory")
; #define PG8_WAIT_L(n) asm volatile("s_waitcnt lgkmcnt(" #n ")" ::: "memory")
; #define PG8_BAR __builtin_amdgcn_s_barrier()
; #define PG8_SCHED __builtin_amdgcn_sched_barrier(0)
; template <class Epi, class Sched>
; __device__ __forceinline__ void gemm_phase(LAS unsigned char* lds, const Gemm g, const Sched& S, const Epi& E, const int wave_s) {
;     ...
;             PG8_WAIT_V(8); PG8_WAIT_L(0); PG8_BAR; PG8_MMA(1, 0, At, B0); PG8_MMA(1, 1, At, B1); PG8_BAR; PG8_SCHED;
;             PG8_LDB(B0, 1, 0); PG8_LDB(B1, 1, 1); PG8_SCHED; PG8_LDA(At, 1, 0); PG8_STAGE(PG8_SA(0, 1), a2 + hstepA, voffA);
;             PG8_WAIT_V(8); PG8_WAIT_L(0); PG8_BAR; PG8_MMA(0, 0, At, B0); PG8_MMA(0, 1, At, B1); PG8_BAR; PG8_SCHED;
	s_nop 0
	v_mfma_f32_16x16x32_bf16 v[92:95], v[100:103], v[160:163], v[92:95]
	v_mfma_f32_16x16x32_bf16 v[88:91], v[136:139], v[160:163], v[88:91]
	v_mfma_f32_16x16x32_bf16 v[84:87], v[100:103], v[186:189], v[84:87]
	v_mfma_f32_16x16x32_bf16 v[80:83], v[136:139], v[186:189], v[80:83]
	v_mfma_f32_16x16x32_bf16 v[76:79], v[100:103], v[194:197], v[76:79]
	v_mfma_f32_16x16x32_bf16 v[72:75], v[136:139], v[194:197], v[72:75]
	v_mfma_f32_16x16x32_bf16 v[68:71], v[100:103], v[202:205], v[68:71]
	v_mfma_f32_16x16x32_bf16 v[64:67], v[136:139], v[202:205], v[64:67]
	v_mfma_f32_16x16x32_bf16 v[92:95], v[108:111], v[164:167], v[92:95]
	v_mfma_f32_16x16x32_bf16 v[88:91], v[140:143], v[164:167], v[88:91]
	v_mfma_f32_16x16x32_bf16 v[84:87], v[108:111], v[190:193], v[84:87]
	v_mfma_f32_16x16x32_bf16 v[80:83], v[140:143], v[190:193], v[80:83]
	v_mfma_f32_16x16x32_bf16 v[76:79], v[108:111], v[198:201], v[76:79]
	v_mfma_f32_16x16x32_bf16 v[72:75], v[140:143], v[198:201], v[72:75]
	v_mfma_f32_16x16x32_bf16 v[68:71], v[108:111], v[216:219], v[68:71]
	v_mfma_f32_16x16x32_bf16 v[64:67], v[140:143], v[216:219], v[64:67]
	s_nop 0
	s_nop 0
	v_mfma_f32_16x16x32_bf16 v[28:31], v[144:147], v[160:163], v[28:31]
	v_mfma_f32_16x16x32_bf16 v[24:27], v[152:155], v[160:163], v[24:27]
	v_mfma_f32_16x16x32_bf16 v[20:23], v[144:147], v[186:189], v[20:23]
	v_mfma_f32_16x16x32_bf16 v[16:19], v[152:155], v[186:189], v[16:19]
	v_mfma_f32_16x16x32_bf16 v[12:15], v[144:147], v[194:197], v[12:15]
	v_mfma_f32_16x16x32_bf16 v[8:11], v[152:155], v[194:197], v[8:11]
	v_mfma_f32_16x16x32_bf16 v[4:7], v[144:147], v[202:205], v[4:7]
	v_mfma_f32_16x16x32_bf16 v[0:3], v[152:155], v[202:205], v[0:3]
	v_mfma_f32_16x16x32_bf16 v[28:31], v[148:151], v[164:167], v[28:31]
	v_mfma_f32_16x16x32_bf16 v[24:27], v[156:159], v[164:167], v[24:27]
	v_mfma_f32_16x16x32_bf16 v[20:23], v[148:151], v[190:193], v[20:23]
	v_mfma_f32_16x16x32_bf16 v[16:19], v[156:159], v[190:193], v[16:19]
	v_mfma_f32_16x16x32_bf16 v[12:15], v[148:151], v[198:201], v[12:15]
	v_mfma_f32_16x16x32_bf16 v[8:11], v[156:159], v[198:201], v[8:11]
	v_mfma_f32_16x16x32_bf16 v[4:7], v[148:151], v[216:219], v[4:7]
	v_mfma_f32_16x16x32_bf16 v[0:3], v[156:159], v[216:219], v[0:3]
	s_nop 0
	s_barrier
	s_add_i32 s55, 0, 0x18000
	s_add_i32 s56, 0, 0x1c000
	v_add_u32_e32 v140, s55, v210
	v_add_u32_e32 v156, s56, v210
	ds_read_b128 v[100:103], v140
	ds_read_b128 v[108:111], v140 offset:1024
	ds_read_b128 v[136:139], v140 offset:2048
	ds_read_b128 v[140:143], v140 offset:3072
	ds_read_b128 v[144:147], v156
	ds_read_b128 v[148:151], v156 offset:1024
	ds_read_b128 v[152:155], v156 offset:2048
	ds_read_b128 v[156:159], v156 offset:3072
	s_add_u32 s42, s42, 0x40000
	s_addc_u32 s43, s43, 0
	s_mov_b32 m0, s44
	v_lshl_add_u64 v[226:227], s[42:43], 0, v[168:169]
	ds_read_b128 v[160:163], v214 offset:32768
	ds_read_b128 v[164:167], v214 offset:33792
	ds_read_b128 v[186:189], v214 offset:34816
	ds_read_b128 v[190:193], v214 offset:35840
	ds_read_b128 v[194:197], v214 offset:36864
	ds_read_b128 v[198:201], v214 offset:37888
	ds_read_b128 v[202:205], v214 offset:38912
	ds_read_b128 v[216:219], v214 offset:39936
	global_load_lds_dwordx4 v[226:227], off
	v_lshl_add_u64 v[226:227], s[42:43], 0, v[172:173]
	s_mov_b32 m0, s45
	s_nop 0
	global_load_lds_dwordx4 v[226:227], off
	s_waitcnt vmcnt(8) lgkmcnt(0)
	s_barrier
	s_nop 0
	v_mfma_f32_16x16x32_bf16 v[132:135], v[100:103], v[160:163], v[132:135]
	v_mfma_f32_16x16x32_bf16 v[128:131], v[136:139], v[160:163], v[128:131]
	v_mfma_f32_16x16x32_bf16 v[124:127], v[100:103], v[186:189], v[124:127]
	v_mfma_f32_16x16x32_bf16 v[120:123], v[136:139], v[186:189], v[120:123]
	v_mfma_f32_16x16x32_bf16 v[116:119], v[100:103], v[194:197], v[116:119]
	v_mfma_f32_16x16x32_bf16 v[112:115], v[136:139], v[194:197], v[112:115]
	v_mfma_f32_16x16x32_bf16 v[104:107], v[100:103], v[202:205], v[104:107]
	v_mfma_f32_16x16x32_bf16 v[96:99], v[136:139], v[202:205], v[96:99]
	v_mfma_f32_16x16x32_bf16 v[132:135], v[108:111], v[164:167], v[132:135]
	v_mfma_f32_16x16x32_bf16 v[128:131], v[140:143], v[164:167], v[128:131]
	v_mfma_f32_16x16x32_bf16 v[124:127], v[108:111], v[190:193], v[124:127]
	v_mfma_f32_16x16x32_bf16 v[120:123], v[140:143], v[190:193], v[120:123]
	v_mfma_f32_16x16x32_bf16 v[116:119], v[108:111], v[198:201], v[116:119]
	v_mfma_f32_16x16x32_bf16 v[112:115], v[140:143], v[198:201], v[112:115]
	v_mfma_f32_16x16x32_bf16 v[104:107], v[108:111], v[216:219], v[104:107]
	v_mfma_f32_16x16x32_bf16 v[96:99], v[140:143], v[216:219], v[96:99]
	s_nop 0
	s_nop 0
	v_mfma_f32_16x16x32_bf16 v[60:63], v[144:147], v[160:163], v[60:63]
	v_mfma_f32_16x16x32_bf16 v[56:59], v[152:155], v[160:163], v[56:59]
	v_mfma_f32_16x16x32_bf16 v[52:55], v[144:147], v[186:189], v[52:55]
	v_mfma_f32_16x16x32_bf16 v[48:51], v[152:155], v[186:189], v[48:51]
	v_mfma_f32_16x16x32_bf16 v[44:47], v[144:147], v[194:197], v[44:47]
	v_mfma_f32_16x16x32_bf16 v[40:43], v[152:155], v[194:197], v[40:43]
	v_mfma_f32_16x16x32_bf16 v[36:39], v[144:147], v[202:205], v[36:39]
	v_mfma_f32_16x16x32_bf16 v[32:35], v[152:155], v[202:205], v[32:35]
	v_mfma_f32_16x16x32_bf16 v[60:63], v[148:151], v[164:167], v[60:63]
	v_mfma_f32_16x16x32_bf16 v[56:59], v[156:159], v[164:167], v[56:59]
	v_mfma_f32_16x16x32_bf16 v[52:55], v[148:151], v[190:193], v[52:55]
	v_mfma_f32_16x16x32_bf16 v[48:51], v[156:159], v[190:193], v[48:51]
	v_mfma_f32_16x16x32_bf16 v[44:47], v[148:151], v[198:201], v[44:47]
	v_mfma_f32_16x16x32_bf16 v[40:43], v[156:159], v[198:201], v[40:43]
	v_mfma_f32_16x16x32_bf16 v[36:39], v[148:151], v[216:219], v[36:39]
	v_mfma_f32_16x16x32_bf16 v[32:35], v[156:159], v[216:219], v[32:35]
	s_nop 0
	s_barrier
; #define PG8_STAGE(bufoff, gbase, voff) do { _Pragma("unroll") for (int _i = 0; _i < 2; ++_i) \
;         __builtin_amdgcn_global_load_lds((const unsigned*)((const char*)(gbase) + (voff)[_i]), (LAS unsigned*)(lds + (bufoff) + ldsw + _i * 8192), 16, 0, 0); } while (0)
; #define PG8_LDA(dst, b, h) do { _Pragma("unroll") for (int m = 0; m < 4; ++m) _Pragma("unroll") for (int k = 0; k < 2; ++k) dst[m][k] = *(const LAS bf16x8*)(lds + PG8_SA(b, h) + aoff + m * 2048 + k * 1024); } while (0)
; #define PG8_MMA(ai, bj, At, Bt) do { __builtin_amdgcn_s_setprio(1); _Pragma("unroll") for (int m = 0; m < 4; ++m) _Pragma("unroll") for (int n = 0; n < 2; ++n) _Pragma("unroll") for (int k = 0; k < 2; ++k) \
;         acc[ai][bj][m][n] = __builtin_amdgcn_mfma_f32_16x16x32_bf16(Bt[n][k], At[m][k], acc[ai][bj][m][n], 0, 0, 0); __builtin_amdgcn_s_setprio(0); } while (0)
; #define PG8_WAIT_V(n) asm volatile("s_waitcnt vmcnt(" #n ")" ::: "memory")
; #define PG8_WAIT_L(n) asm volatile("s_waitcnt lgkmcnt(" #n ")" ::: "memory")
; #define PG8_BAR __builtin_amdgcn_s_barrier()
; #define PG8_SCHED __builtin_amdgcn_sched_barrier(0)
; template <class Epi, class Sched>
; __device__ __forceinline__ void gemm_phase(LAS unsigned char* lds, const Gemm g, const Sched& S, const Epi& E, const int wave_s) {
;     ...
;             PG8_LDA(At, 1, 1); PG8_STAGE(PG8_SB(1, 0), b3, voffB); PG8_STAGE(PG8_SB(1, 1), b3 + hstepB, voffB); PG8_STAGE(PG8_SA(1, 0), a3, voffA);
;             PG8_WAIT_V(8); PG8_WAIT_L(0); PG8_BAR; PG8_MMA(1, 0, At, B0); PG8_MMA(1, 1, At, B1); PG8_BAR; PG8_SCHED;
;         }
	s_add_i32 s42, s55, s81
	v_lshl_add_u64 v[206:207], v[206:207], 0, s[22:23]
	s_mov_b32 m0, s42
	ds_read_b128 v[160:163], v214 offset:49152
	ds_read_b128 v[164:167], v214 offset:50176
	ds_read_b128 v[186:189], v214 offset:51200
	ds_read_b128 v[190:193], v214 offset:52224
	ds_read_b128 v[194:197], v214 offset:53248
	ds_read_b128 v[198:201], v214 offset:54272
	ds_read_b128 v[202:205], v214 offset:55296
	ds_read_b128 v[216:219], v214 offset:56320
	global_load_lds_dwordx4 v[206:207], off
	s_add_i32 m0, s42, 0x2000
	s_add_u32 s4, s4, 0x40080
	v_lshl_add_u64 v[206:207], v[220:221], 0, s[22:23]
	s_addc_u32 s5, s5, 0
	s_add_i32 s42, s56, s81
	global_load_lds_dwordx4 v[206:207], off
	v_lshl_add_u64 v[206:207], s[4:5], 0, v[170:171]
	s_mov_b32 m0, s42
	s_nop 0
	global_load_lds_dwordx4 v[206:207], off
	v_lshl_add_u64 v[206:207], s[4:5], 0, v[174:175]
	s_add_i32 m0, s42, 0x2000
	s_nop 0
	global_load_lds_dwordx4 v[206:207], off
	v_lshl_add_u64 v[206:207], v[222:223], 0, s[22:23]
	s_mov_b32 m0, s47
	s_nop 0
	global_load_lds_dwordx4 v[206:207], off
	v_lshl_add_u64 v[206:207], v[224:225], 0, s[22:23]
	s_mov_b32 m0, s48
	s_nop 0
	global_load_lds_dwordx4 v[206:207], off
	s_waitcnt vmcnt(8) lgkmcnt(0)
	s_barrier
	s_nop 0
	v_mfma_f32_16x16x32_bf16 v[92:95], v[100:103], v[160:163], v[92:95]
	v_mfma_f32_16x16x32_bf16 v[88:91], v[136:139], v[160:163], v[88:91]
	v_mfma_f32_16x16x32_bf16 v[84:87], v[100:103], v[186:189], v[84:87]
	v_mfma_f32_16x16x32_bf16 v[80:83], v[136:139], v[186:189], v[80:83]
	v_mfma_f32_16x16x32_bf16 v[76:79], v[100:103], v[194:197], v[76:79]
	v_mfma_f32_16x16x32_bf16 v[72:75], v[136:139], v[194:197], v[72:75]
	v_mfma_f32_16x16x32_bf16 v[68:71], v[100:103], v[202:205], v[68:71]
	v_mfma_f32_16x16x32_bf16 v[64:67], v[136:139], v[202:205], v[64:67]
	v_mfma_f32_16x16x32_bf16 v[92:95], v[108:111], v[164:167], v[92:95]
	v_mfma_f32_16x16x32_bf16 v[88:91], v[140:143], v[164:167], v[88:91]
	v_mfma_f32_16x16x32_bf16 v[84:87], v[108:111], v[190:193], v[84:87]
	v_mfma_f32_16x16x32_bf16 v[80:83], v[140:143], v[190:193], v[80:83]
	v_mfma_f32_16x16x32_bf16 v[76:79], v[108:111], v[198:201], v[76:79]
	v_mfma_f32_16x16x32_bf16 v[72:75], v[140:143], v[198:201], v[72:75]
	v_mfma_f32_16x16x32_bf16 v[68:71], v[108:111], v[216:219], v[68:71]
	v_mfma_f32_16x16x32_bf16 v[64:67], v[140:143], v[216:219], v[64:67]
	s_nop 0
	s_nop 0
	v_mfma_f32_16x16x32_bf16 v[28:31], v[144:147], v[160:163], v[28:31]
	v_mfma_f32_16x16x32_bf16 v[24:27], v[152:155], v[160:163], v[24:27]
	v_mfma_f32_16x16x32_bf16 v[20:23], v[144:147], v[186:189], v[20:23]
	v_mfma_f32_16x16x32_bf16 v[16:19], v[152:155], v[186:189], v[16:19]
	v_mfma_f32_16x16x32_bf16 v[12:15], v[144:147], v[194:197], v[12:15]
	v_mfma_f32_16x16x32_bf16 v[8:11], v[152:155], v[194:197], v[8:11]
	v_mfma_f32_16x16x32_bf16 v[4:7], v[144:147], v[202:205], v[4:7]
	v_mfma_f32_16x16x32_bf16 v[0:3], v[152:155], v[202:205], v[0:3]
	v_mfma_f32_16x16x32_bf16 v[28:31], v[148:151], v[164:167], v[28:31]
	v_mfma_f32_16x16x32_bf16 v[24:27], v[156:159], v[164:167], v[24:27]
	v_mfma_f32_16x16x32_bf16 v[20:23], v[148:151], v[190:193], v[20:23]
	v_mfma_f32_16x16x32_bf16 v[16:19], v[156:159], v[190:193], v[16:19]
	v_mfma_f32_16x16x32_bf16 v[12:15], v[148:151], v[198:201], v[12:15]
	v_mfma_f32_16x16x32_bf16 v[8:11], v[156:159], v[198:201], v[8:11]
	v_mfma_f32_16x16x32_bf16 v[4:7], v[148:151], v[216:219], v[4:7]
	v_mfma_f32_16x16x32_bf16 v[0:3], v[156:159], v[216:219], v[0:3]
	s_nop 0
	s_barrier
	s_add_i32 s54, s54, 2
	s_add_u32 s40, s40, 0x100
	s_addc_u32 s41, s41, 0
	s_add_u32 s39, s39, 0x100
	s_addc_u32 s53, s53, 0
	s_cmp_gt_u32 s54, 13
	s_cbranch_scc0 .LBB0_860
	s_and_b64 vcc, exec, s[24:25]
	s_cbranch_vccz .LBB0_863
	s_barrier

; #define PG8_STAGE(bufoff, gbase, voff) do { _Pragma("unroll") for (int _i = 0; _i < 2; ++_i) \
;         __builtin_amdgcn_global_load_lds((const unsigned*)((const char*)(gbase) + (voff)[_i]), (LAS unsigned*)(lds + (bufoff) + ldsw + _i * 8192), 16, 0, 0); } while (0)
; #define PG8_LDA(dst, b, h) do { _Pragma("unroll") for (int m = 0; m < 4; ++m) _Pragma("unroll") for (int k = 0; k < 2; ++k) dst[m][k] = *(const LAS bf16x8*)(lds + PG8_SA(b, h) + aoff + m * 2048 + k * 1024); } while (0)
; #define PG8_LDB(dst, b, h) do { _Pragma("unroll") for (int n = 0; n < 2; ++n) _Pragma("unroll") for (int k = 0; k < 2; ++k) dst[n][k] = *(const LAS bf16x8*)(lds + PG8_SB(b, h) + boff + n * 2048 + k * 1024); } while (0)
; #define PG8_MMA(ai, bj, At, Bt) do { __builtin_amdgcn_s_setprio(1); _Pragma("unroll") for (int m = 0; m < 4; ++m) _Pragma("unroll") for (int n = 0; n < 2; ++n) _Pragma("unroll") for (int k = 0; k < 2; ++k) \
;         acc[ai][bj][m][n] = __builtin_amdgcn_mfma_f32_16x16x32_bf16(Bt[n][k], At[m][k], acc[ai][bj][m][n], 0, 0, 0); __builtin_amdgcn_s_setprio(0); } while (0)
; #define PG8_WAIT_V(n) asm volatile("s_waitcnt vmcnt(" #n ")" ::: "memory")
; #define PG8_WAIT_L(n) asm volatile("s_waitcnt lgkmcnt(" #n ")" ::: "memory")
; #define PG8_BAR __builtin_amdgcn_s_barrier()
; #define PG8_SCHED __builtin_amdgcn_sched_barrier(0)
; template <class Epi, class Sched>
; __device__ __forceinline__ void gemm_phase(LAS unsigned char* lds, const Gemm g, const Sched& S, const Epi& E, const int wave_s) {
;     ...
;             const bool last = (t == nt - 2);
;             const char* a1 = cA + (size_t)(t + 1) * kstep;
;             const char* a2 = last ? nA : cA + (size_t)(t + 2) * kstep; const char* b2 = last ? nB : cB + (size_t)(t + 2) * kstep;
;             const char* a3 = a2 + kstep; const char* b3 = b2 + kstep;
;             PG8_LDB(B0, 0, 0); PG8_LDB(B1, 0, 1); PG8_SCHED; PG8_LDA(At, 0, 0); PG8_STAGE(PG8_SA(1, 1), a1 + hstepA, voffA);
;             PG8_WAIT_V(8); PG8_WAIT_L(0); PG8_BAR; PG8_MMA(0, 0, At, B0); PG8_MMA(0, 1, At, B1); PG8_BAR; PG8_SCHED;
;             PG8_LDA(At, 0, 1); PG8_STAGE(PG8_SB(0, 0), b2, voffB); PG8_STAGE(PG8_SB(0, 1), b2 + hstepB, voffB); PG8_STAGE(PG8_SA(0, 0), a2, voffA);
;             PG8_WAIT_V(8); PG8_WAIT_L(0); PG8_BAR; PG8_MMA(1, 0, At, B0); PG8_MMA(1, 1, At, B1); PG8_BAR; PG8_SCHED;
.LBB0_1024:
	s_add_u32 s48, s64, s46
	s_addc_u32 s49, s65, s47
	s_add_u32 s48, s48, 0x99a5200
	s_addc_u32 s49, s49, 0
	s_add_u32 s73, s70, s46
	s_addc_u32 s74, s71, s47
	s_add_i32 s75, 0, 0x10000
	s_cmpk_eq_i32 s46, 0x700
	s_cselect_b32 s51, s11, s49
	s_cselect_b32 s50, s10, s48
	v_add_u32_e32 v128, s75, v178
	s_cselect_b32 s49, s68, s74
	s_cselect_b32 s48, s69, s73
	s_add_i32 s73, 0, 0x14000
	ds_read_b128 v[170:173], v128
	ds_read_b128 v[182:185], v128 offset:1024
	ds_read_b128 v[186:189], v128 offset:2048
	ds_read_b128 v[190:193], v128 offset:3072
	v_add_u32_e32 v128, s73, v178
	ds_read_b128 v[194:197], v128
	ds_read_b128 v[198:201], v128 offset:1024
	ds_read_b128 v[202:205], v128 offset:2048
	ds_read_b128 v[206:209], v128 offset:3072
	v_lshl_add_u64 v[242:243], v[166:167], 0, s[46:47]
	s_add_i32 m0, s52, 0xc000
	ds_read_b128 v[210:213], v180
	ds_read_b128 v[214:217], v180 offset:1024
	ds_read_b128 v[218:221], v180 offset:2048
	ds_read_b128 v[222:225], v180 offset:3072
	ds_read_b128 v[226:229], v180 offset:4096
	ds_read_b128 v[230:233], v180 offset:5120
	ds_read_b128 v[234:237], v180 offset:6144
	ds_read_b128 v[238:241], v180 offset:7168
	global_load_lds_dwordx4 v[242:243], off
	v_lshl_add_u64 v[242:243], v[168:169], 0, s[46:47]
	s_add_i32 m0, s52, 0xe000
	s_nop 0
	global_load_lds_dwordx4 v[242:243], off
	s_waitcnt vmcnt(8) lgkmcnt(0)
	s_barrier
	s_nop 0
	v_mfma_f32_16x16x32_bf16 v[124:127], v[170:173], v[210:213], v[124:127]
	v_mfma_f32_16x16x32_bf16 v[120:123], v[186:189], v[210:213], v[120:123]
	v_mfma_f32_16x16x32_bf16 v[116:119], v[170:173], v[218:221], v[116:119]
	v_mfma_f32_16x16x32_bf16 v[112:115], v[186:189], v[218:221], v[112:115]
	v_mfma_f32_16x16x32_bf16 v[108:111], v[170:173], v[226:229], v[108:111]
	v_mfma_f32_16x16x32_bf16 v[100:103], v[186:189], v[226:229], v[100:103]
	v_mfma_f32_16x16x32_bf16 v[92:95], v[170:173], v[234:237], v[92:95]
	v_mfma_f32_16x16x32_bf16 v[84:87], v[186:189], v[234:237], v[84:87]
	v_mfma_f32_16x16x32_bf16 v[124:127], v[182:185], v[214:217], v[124:127]
	v_mfma_f32_16x16x32_bf16 v[120:123], v[190:193], v[214:217], v[120:123]
	v_mfma_f32_16x16x32_bf16 v[116:119], v[182:185], v[222:225], v[116:119]
	v_mfma_f32_16x16x32_bf16 v[112:115], v[190:193], v[222:225], v[112:115]
	v_mfma_f32_16x16x32_bf16 v[108:111], v[182:185], v[230:233], v[108:111]
	v_mfma_f32_16x16x32_bf16 v[100:103], v[190:193], v[230:233], v[100:103]
	v_mfma_f32_16x16x32_bf16 v[92:95], v[182:185], v[238:241], v[92:95]
	v_mfma_f32_16x16x32_bf16 v[84:87], v[190:193], v[238:241], v[84:87]
	s_nop 0
	s_nop 0
	v_mfma_f32_16x16x32_bf16 v[104:107], v[194:197], v[210:213], v[104:107]
	v_mfma_f32_16x16x32_bf16 v[96:99], v[202:205], v[210:213], v[96:99]
	v_mfma_f32_16x16x32_bf16 v[88:91], v[194:197], v[218:221], v[88:91]
	v_mfma_f32_16x16x32_bf16 v[80:83], v[202:205], v[218:221], v[80:83]
	v_mfma_f32_16x16x32_bf16 v[76:79], v[194:197], v[226:229], v[76:79]
	v_mfma_f32_16x16x32_bf16 v[72:75], v[202:205], v[226:229], v[72:75]
	v_mfma_f32_16x16x32_bf16 v[68:71], v[194:197], v[234:237], v[68:71]
	v_mfma_f32_16x16x32_bf16 v[64:67], v[202:205], v[234:237], v[64:67]
	v_mfma_f32_16x16x32_bf16 v[104:107], v[198:201], v[214:217], v[104:107]
	v_mfma_f32_16x16x32_bf16 v[96:99], v[206:209], v[214:217], v[96:99]
	v_mfma_f32_16x16x32_bf16 v[88:91], v[198:201], v[222:225], v[88:91]
	v_mfma_f32_16x16x32_bf16 v[80:83], v[206:209], v[222:225], v[80:83]
	v_mfma_f32_16x16x32_bf16 v[76:79], v[198:201], v[230:233], v[76:79]
	v_mfma_f32_16x16x32_bf16 v[72:75], v[206:209], v[230:233], v[72:75]
	v_mfma_f32_16x16x32_bf16 v[68:71], v[198:201], v[238:241], v[68:71]
	v_mfma_f32_16x16x32_bf16 v[64:67], v[206:209], v[238:241], v[64:67]
	s_nop 0
	s_barrier
	s_add_i32 s74, s75, s81
	v_lshl_add_u64 v[242:243], s[48:49], 0, v[130:131]
	s_mov_b32 m0, s74
	ds_read_b128 v[210:213], v180 offset:16384
	ds_read_b128 v[214:217], v180 offset:17408
	ds_read_b128 v[218:221], v180 offset:18432
	ds_read_b128 v[222:225], v180 offset:19456
	ds_read_b128 v[226:229], v180 offset:20480
	ds_read_b128 v[230:233], v180 offset:21504
	ds_read_b128 v[234:237], v180 offset:22528
	ds_read_b128 v[238:241], v180 offset:23552
	global_load_lds_dwordx4 v[242:243], off
	s_add_i32 m0, s74, 0x2000
	s_add_u32 s74, s48, 0x40000
	v_lshl_add_u64 v[244:245], s[48:49], 0, v[132:133]
	s_addc_u32 s75, s49, 0
	s_add_i32 s73, s73, s81
	global_load_lds_dwordx4 v[244:245], off
	v_lshl_add_u64 v[246:247], s[74:75], 0, v[130:131]
	s_mov_b32 m0, s73
	v_lshl_add_u64 v[248:249], s[50:51], 0, v[132:133]
	global_load_lds_dwordx4 v[246:247], off
	v_lshl_add_u64 v[246:247], s[74:75], 0, v[132:133]
	s_add_i32 m0, s73, 0x2000
	s_nop 0
	global_load_lds_dwordx4 v[246:247], off
	v_lshl_add_u64 v[246:247], s[50:51], 0, v[130:131]
	s_mov_b32 m0, s52
	s_nop 0
	global_load_lds_dwordx4 v[246:247], off
	s_mov_b32 m0, s57
	s_nop 0
	global_load_lds_dwordx4 v[248:249], off
	s_waitcnt vmcnt(8) lgkmcnt(0)
	s_barrier
; #define PG8_STAGE(bufoff, gbase, voff) do { _Pragma("unroll") for (int _i = 0; _i < 2; ++_i) \
;         __builtin_amdgcn_global_load_lds((const unsigned*)((const char*)(gbase) + (voff)[_i]), (LAS unsigned*)(lds + (bufoff) + ldsw + _i * 8192), 16, 0, 0); } while (0)
; #define PG8_LDA(dst, b, h) do { _Pragma("unroll") for (int m = 0; m < 4; ++m) _Pragma("unroll") for (int k = 0; k < 2; ++k) dst[m][k] = *(const LAS bf16x8*)(lds + PG8_SA(b, h) + aoff + m * 2048 + k * 1024); } while (0)
; #define PG8_LDB(dst, b, h) do { _Pragma("unroll") for (int n = 0; n < 2; ++n) _Pragma("unroll") for (int k = 0; k < 2; ++k) dst[n][k] = *(const LAS bf16x8*)(lds + PG8_SB(b, h) + boff + n * 2048 + k * 1024); } while (0)
; #define PG8_MMA(ai, bj, At, Bt) do { __builtin_amdgcn_s_setprio(1); _Pragma("unroll") for (int m = 0; m < 4; ++m) _Pragma("unroll") for (int n = 0; n < 2; ++n) _Pragma("unroll") for (int k = 0; k < 2; ++k) \
;         acc[ai][bj][m][n] = __builtin_amdgcn_mfma_f32_16x16x32_bf16(Bt[n][k], At[m][k], acc[ai][bj][m][n], 0, 0, 0); __builtin_amdgcn_s_setprio(0); } while (0)
; #define PG8_WAIT_V(n) asm volatile("s_waitcnt vmcnt(" #n ")" ::: "memory")
; #define PG8_WAIT_L(n) asm volatile("s_waitcnt lgkmcnt(" #n ")" ::: "memory")
; #define PG8_BAR __builtin_amdgcn_s_barrier()
; #define PG8_SCHED __builtin_amdgcn_sched_barrier(0)
; template <class Epi, class Sched>
; __device__ __forceinline__ void gemm_phase(LAS unsigned char* lds, const Gemm g, const Sched& S, const Epi& E, const int wave_s) {
;     ...
;             PG8_WAIT_V(8); PG8_WAIT_L(0); PG8_BAR; PG8_MMA(1, 0, At, B0); PG8_MMA(1, 1, At, B1); PG8_BAR; PG8_SCHED;
;             PG8_LDB(B0, 1, 0); PG8_LDB(B1, 1, 1); PG8_SCHED; PG8_LDA(At, 1, 0); PG8_STAGE(PG8_SA(0, 1), a2 + hstepA, voffA);
;             PG8_WAIT_V(8); PG8_WAIT_L(0); PG8_BAR; PG8_MMA(0, 0, At, B0); PG8_MMA(0, 1, At, B1); PG8_BAR; PG8_SCHED;
	s_nop 0
	v_mfma_f32_16x16x32_bf16 v[60:63], v[170:173], v[210:213], v[60:63]
	v_mfma_f32_16x16x32_bf16 v[56:59], v[186:189], v[210:213], v[56:59]
	v_mfma_f32_16x16x32_bf16 v[52:55], v[170:173], v[218:221], v[52:55]
	v_mfma_f32_16x16x32_bf16 v[48:51], v[186:189], v[218:221], v[48:51]
	v_mfma_f32_16x16x32_bf16 v[44:47], v[170:173], v[226:229], v[44:47]
	v_mfma_f32_16x16x32_bf16 v[36:39], v[186:189], v[226:229], v[36:39]
	v_mfma_f32_16x16x32_bf16 v[28:31], v[170:173], v[234:237], v[28:31]
	v_mfma_f32_16x16x32_bf16 v[20:23], v[186:189], v[234:237], v[20:23]
	v_mfma_f32_16x16x32_bf16 v[60:63], v[182:185], v[214:217], v[60:63]
	v_mfma_f32_16x16x32_bf16 v[56:59], v[190:193], v[214:217], v[56:59]
	v_mfma_f32_16x16x32_bf16 v[52:55], v[182:185], v[222:225], v[52:55]
	v_mfma_f32_16x16x32_bf16 v[48:51], v[190:193], v[222:225], v[48:51]
	v_mfma_f32_16x16x32_bf16 v[44:47], v[182:185], v[230:233], v[44:47]
	v_mfma_f32_16x16x32_bf16 v[36:39], v[190:193], v[230:233], v[36:39]
	v_mfma_f32_16x16x32_bf16 v[28:31], v[182:185], v[238:241], v[28:31]
	v_mfma_f32_16x16x32_bf16 v[20:23], v[190:193], v[238:241], v[20:23]
	s_nop 0
	s_nop 0
	v_mfma_f32_16x16x32_bf16 v[40:43], v[194:197], v[210:213], v[40:43]
	v_mfma_f32_16x16x32_bf16 v[32:35], v[202:205], v[210:213], v[32:35]
	v_mfma_f32_16x16x32_bf16 v[24:27], v[194:197], v[218:221], v[24:27]
	v_mfma_f32_16x16x32_bf16 v[16:19], v[202:205], v[218:221], v[16:19]
	v_mfma_f32_16x16x32_bf16 v[12:15], v[194:197], v[226:229], v[12:15]
	v_mfma_f32_16x16x32_bf16 v[8:11], v[202:205], v[226:229], v[8:11]
	v_mfma_f32_16x16x32_bf16 v[4:7], v[194:197], v[234:237], v[4:7]
	v_mfma_f32_16x16x32_bf16 v[0:3], v[202:205], v[234:237], v[0:3]
	v_mfma_f32_16x16x32_bf16 v[40:43], v[198:201], v[214:217], v[40:43]
	v_mfma_f32_16x16x32_bf16 v[32:35], v[206:209], v[214:217], v[32:35]
	v_mfma_f32_16x16x32_bf16 v[24:27], v[198:201], v[222:225], v[24:27]
	v_mfma_f32_16x16x32_bf16 v[16:19], v[206:209], v[222:225], v[16:19]
	v_mfma_f32_16x16x32_bf16 v[12:15], v[198:201], v[230:233], v[12:15]
	v_mfma_f32_16x16x32_bf16 v[8:11], v[206:209], v[230:233], v[8:11]
	v_mfma_f32_16x16x32_bf16 v[4:7], v[198:201], v[238:241], v[4:7]
	v_mfma_f32_16x16x32_bf16 v[0:3], v[206:209], v[238:241], v[0:3]
	s_nop 0
	s_barrier
	s_add_i32 s73, 0, 0x18000
	v_add_u32_e32 v128, s73, v178
	s_add_i32 s74, 0, 0x1c000
	ds_read_b128 v[170:173], v128
	ds_read_b128 v[182:185], v128 offset:1024
	ds_read_b128 v[186:189], v128 offset:2048
	ds_read_b128 v[190:193], v128 offset:3072
	v_add_u32_e32 v128, s74, v178
	ds_read_b128 v[194:197], v128
	ds_read_b128 v[198:201], v128 offset:1024
	ds_read_b128 v[202:205], v128 offset:2048
	ds_read_b128 v[206:209], v128 offset:3072
	s_add_u32 s50, s50, 0x40000
	s_addc_u32 s51, s51, 0
	s_mov_b32 m0, s58
	v_lshl_add_u64 v[250:251], s[50:51], 0, v[130:131]
	ds_read_b128 v[210:213], v180 offset:32768
	ds_read_b128 v[214:217], v180 offset:33792
	ds_read_b128 v[218:221], v180 offset:34816
	ds_read_b128 v[222:225], v180 offset:35840
	ds_read_b128 v[226:229], v180 offset:36864
	ds_read_b128 v[230:233], v180 offset:37888
	ds_read_b128 v[234:237], v180 offset:38912
	ds_read_b128 v[238:241], v180 offset:39936
	global_load_lds_dwordx4 v[250:251], off
	v_lshl_add_u64 v[250:251], s[50:51], 0, v[132:133]
	s_mov_b32 m0, s59
	s_nop 0
	global_load_lds_dwordx4 v[250:251], off
	s_waitcnt vmcnt(8) lgkmcnt(0)
	s_barrier
	s_nop 0
	v_mfma_f32_16x16x32_bf16 v[124:127], v[170:173], v[210:213], v[124:127]
	v_mfma_f32_16x16x32_bf16 v[120:123], v[186:189], v[210:213], v[120:123]
	v_mfma_f32_16x16x32_bf16 v[116:119], v[170:173], v[218:221], v[116:119]
	v_mfma_f32_16x16x32_bf16 v[112:115], v[186:189], v[218:221], v[112:115]
	v_mfma_f32_16x16x32_bf16 v[108:111], v[170:173], v[226:229], v[108:111]
	v_mfma_f32_16x16x32_bf16 v[100:103], v[186:189], v[226:229], v[100:103]
	v_mfma_f32_16x16x32_bf16 v[92:95], v[170:173], v[234:237], v[92:95]
	v_mfma_f32_16x16x32_bf16 v[84:87], v[186:189], v[234:237], v[84:87]
	v_mfma_f32_16x16x32_bf16 v[124:127], v[182:185], v[214:217], v[124:127]
	v_mfma_f32_16x16x32_bf16 v[120:123], v[190:193], v[214:217], v[120:123]
	v_mfma_f32_16x16x32_bf16 v[116:119], v[182:185], v[222:225], v[116:119]
	v_mfma_f32_16x16x32_bf16 v[112:115], v[190:193], v[222:225], v[112:115]
	v_mfma_f32_16x16x32_bf16 v[108:111], v[182:185], v[230:233], v[108:111]
	v_mfma_f32_16x16x32_bf16 v[100:103], v[190:193], v[230:233], v[100:103]
	v_mfma_f32_16x16x32_bf16 v[92:95], v[182:185], v[238:241], v[92:95]
	v_mfma_f32_16x16x32_bf16 v[84:87], v[190:193], v[238:241], v[84:87]
	s_nop 0
	s_nop 0
	v_mfma_f32_16x16x32_bf16 v[104:107], v[194:197], v[210:213], v[104:107]
	v_mfma_f32_16x16x32_bf16 v[96:99], v[202:205], v[210:213], v[96:99]
	v_mfma_f32_16x16x32_bf16 v[88:91], v[194:197], v[218:221], v[88:91]
	v_mfma_f32_16x16x32_bf16 v[80:83], v[202:205], v[218:221], v[80:83]
	v_mfma_f32_16x16x32_bf16 v[76:79], v[194:197], v[226:229], v[76:79]
	v_mfma_f32_16x16x32_bf16 v[72:75], v[202:205], v[226:229], v[72:75]
	v_mfma_f32_16x16x32_bf16 v[68:71], v[194:197], v[234:237], v[68:71]
	v_mfma_f32_16x16x32_bf16 v[64:67], v[202:205], v[234:237], v[64:67]
	v_mfma_f32_16x16x32_bf16 v[104:107], v[198:201], v[214:217], v[104:107]
	v_mfma_f32_16x16x32_bf16 v[96:99], v[206:209], v[214:217], v[96:99]
	v_mfma_f32_16x16x32_bf16 v[88:91], v[198:201], v[222:225], v[88:91]
	v_mfma_f32_16x16x32_bf16 v[80:83], v[206:209], v[222:225], v[80:83]
	v_mfma_f32_16x16x32_bf16 v[76:79], v[198:201], v[230:233], v[76:79]
	v_mfma_f32_16x16x32_bf16 v[72:75], v[206:209], v[230:233], v[72:75]
	v_mfma_f32_16x16x32_bf16 v[68:71], v[198:201], v[238:241], v[68:71]
	v_mfma_f32_16x16x32_bf16 v[64:67], v[206:209], v[238:241], v[64:67]
	s_nop 0
	s_barrier
; #define PG8_STAGE(bufoff, gbase, voff) do { _Pragma("unroll") for (int _i = 0; _i < 2; ++_i) \
;         __builtin_amdgcn_global_load_lds((const unsigned*)((const char*)(gbase) + (voff)[_i]), (LAS unsigned*)(lds + (bufoff) + ldsw + _i * 8192), 16, 0, 0); } while (0)
; #define PG8_LDA(dst, b, h) do { _Pragma("unroll") for (int m = 0; m < 4; ++m) _Pragma("unroll") for (int k = 0; k < 2; ++k) dst[m][k] = *(const LAS bf16x8*)(lds + PG8_SA(b, h) + aoff + m * 2048 + k * 1024); } while (0)
; #define PG8_MMA(ai, bj, At, Bt) do { __builtin_amdgcn_s_setprio(1); _Pragma("unroll") for (int m = 0; m < 4; ++m) _Pragma("unroll") for (int n = 0; n < 2; ++n) _Pragma("unroll") for (int k = 0; k < 2; ++k) \
;         acc[ai][bj][m][n] = __builtin_amdgcn_mfma_f32_16x16x32_bf16(Bt[n][k], At[m][k], acc[ai][bj][m][n], 0, 0, 0); __builtin_amdgcn_s_setprio(0); } while (0)
; #define PG8_WAIT_V(n) asm volatile("s_waitcnt vmcnt(" #n ")" ::: "memory")
; #define PG8_WAIT_L(n) asm volatile("s_waitcnt lgkmcnt(" #n ")" ::: "memory")
; #define PG8_BAR __builtin_amdgcn_s_barrier()
; #define PG8_SCHED __builtin_amdgcn_sched_barrier(0)
; template <class Epi, class Sched>
; __device__ __forceinline__ void gemm_phase(LAS unsigned char* lds, const Gemm g, const Sched& S, const Epi& E, const int wave_s) {
;     ...
;             PG8_LDA(At, 1, 1); PG8_STAGE(PG8_SB(1, 0), b3, voffB); PG8_STAGE(PG8_SB(1, 1), b3 + hstepB, voffB); PG8_STAGE(PG8_SA(1, 0), a3, voffA);
;             PG8_WAIT_V(8); PG8_WAIT_L(0); PG8_BAR; PG8_MMA(1, 0, At, B0); PG8_MMA(1, 1, At, B1); PG8_BAR; PG8_SCHED;
;         }
;         if (wr == 0) PG8_BAR;
	s_add_i32 s50, s73, s81
	v_lshl_add_u64 v[242:243], v[242:243], 0, s[22:23]
	s_mov_b32 m0, s50
	ds_read_b128 v[210:213], v180 offset:49152
	ds_read_b128 v[214:217], v180 offset:50176
	ds_read_b128 v[218:221], v180 offset:51200
	ds_read_b128 v[222:225], v180 offset:52224
	ds_read_b128 v[226:229], v180 offset:53248
	ds_read_b128 v[230:233], v180 offset:54272
	ds_read_b128 v[234:237], v180 offset:55296
	ds_read_b128 v[238:241], v180 offset:56320
	global_load_lds_dwordx4 v[242:243], off
	s_add_i32 m0, s50, 0x2000
	s_add_u32 s48, s48, 0x40080
	v_lshl_add_u64 v[242:243], v[244:245], 0, s[22:23]
	s_addc_u32 s49, s49, 0
	s_add_i32 s50, s74, s81
	global_load_lds_dwordx4 v[242:243], off
	v_lshl_add_u64 v[242:243], s[48:49], 0, v[130:131]
	s_mov_b32 m0, s50
	s_nop 0
	global_load_lds_dwordx4 v[242:243], off
	v_lshl_add_u64 v[242:243], s[48:49], 0, v[132:133]
	s_add_i32 m0, s50, 0x2000
	s_nop 0
	global_load_lds_dwordx4 v[242:243], off
	v_lshl_add_u64 v[242:243], v[246:247], 0, s[22:23]
	s_mov_b32 m0, s20
	s_nop 0
	global_load_lds_dwordx4 v[242:243], off
	v_lshl_add_u64 v[242:243], v[248:249], 0, s[22:23]
	s_mov_b32 m0, s63
	s_nop 0
	global_load_lds_dwordx4 v[242:243], off
	s_waitcnt vmcnt(8) lgkmcnt(0)
	s_barrier
	s_nop 0
	v_mfma_f32_16x16x32_bf16 v[60:63], v[170:173], v[210:213], v[60:63]
	v_mfma_f32_16x16x32_bf16 v[56:59], v[186:189], v[210:213], v[56:59]
	v_mfma_f32_16x16x32_bf16 v[52:55], v[170:173], v[218:221], v[52:55]
	v_mfma_f32_16x16x32_bf16 v[48:51], v[186:189], v[218:221], v[48:51]
	v_mfma_f32_16x16x32_bf16 v[44:47], v[170:173], v[226:229], v[44:47]
	v_mfma_f32_16x16x32_bf16 v[36:39], v[186:189], v[226:229], v[36:39]
	v_mfma_f32_16x16x32_bf16 v[28:31], v[170:173], v[234:237], v[28:31]
	v_mfma_f32_16x16x32_bf16 v[20:23], v[186:189], v[234:237], v[20:23]
	v_mfma_f32_16x16x32_bf16 v[60:63], v[182:185], v[214:217], v[60:63]
	v_mfma_f32_16x16x32_bf16 v[56:59], v[190:193], v[214:217], v[56:59]
	v_mfma_f32_16x16x32_bf16 v[52:55], v[182:185], v[222:225], v[52:55]
	v_mfma_f32_16x16x32_bf16 v[48:51], v[190:193], v[222:225], v[48:51]
	v_mfma_f32_16x16x32_bf16 v[44:47], v[182:185], v[230:233], v[44:47]
	v_mfma_f32_16x16x32_bf16 v[36:39], v[190:193], v[230:233], v[36:39]
	v_mfma_f32_16x16x32_bf16 v[28:31], v[182:185], v[238:241], v[28:31]
	v_mfma_f32_16x16x32_bf16 v[20:23], v[190:193], v[238:241], v[20:23]
	s_nop 0
	s_nop 0
	v_mfma_f32_16x16x32_bf16 v[40:43], v[194:197], v[210:213], v[40:43]
	v_mfma_f32_16x16x32_bf16 v[32:35], v[202:205], v[210:213], v[32:35]
	v_mfma_f32_16x16x32_bf16 v[24:27], v[194:197], v[218:221], v[24:27]
	v_mfma_f32_16x16x32_bf16 v[16:19], v[202:205], v[218:221], v[16:19]
	v_mfma_f32_16x16x32_bf16 v[12:15], v[194:197], v[226:229], v[12:15]
	v_mfma_f32_16x16x32_bf16 v[8:11], v[202:205], v[226:229], v[8:11]
	v_mfma_f32_16x16x32_bf16 v[4:7], v[194:197], v[234:237], v[4:7]
	v_mfma_f32_16x16x32_bf16 v[0:3], v[202:205], v[234:237], v[0:3]
	v_mfma_f32_16x16x32_bf16 v[40:43], v[198:201], v[214:217], v[40:43]
	v_mfma_f32_16x16x32_bf16 v[32:35], v[206:209], v[214:217], v[32:35]
	v_mfma_f32_16x16x32_bf16 v[24:27], v[198:201], v[222:225], v[24:27]
	v_mfma_f32_16x16x32_bf16 v[16:19], v[206:209], v[222:225], v[16:19]
	v_mfma_f32_16x16x32_bf16 v[12:15], v[198:201], v[230:233], v[12:15]
	v_mfma_f32_16x16x32_bf16 v[8:11], v[206:209], v[230:233], v[8:11]
	v_mfma_f32_16x16x32_bf16 v[4:7], v[198:201], v[238:241], v[4:7]
	v_mfma_f32_16x16x32_bf16 v[0:3], v[206:209], v[238:241], v[0:3]
	s_nop 0
	s_barrier
	s_add_i32 s72, s72, 2
	s_add_u32 s46, s46, 0x100
	s_addc_u32 s47, s47, 0
	s_cmp_gt_u32 s72, 13
	s_cbranch_scc0 .LBB0_1024
	s_and_b64 vcc, exec, s[12:13]
	s_cbranch_vccz .LBB0_1027
	s_barrier
